# combined small edits: packed gate sigmoid, census loads batched, gla gk-row wait moved, gla3 q/k loads hoisted, norm wave sums via DPP, item-tail rebalancing
# speedup vs baseline: 1.0010x; 1.0010x over previous
; DI unsigned pack2(float a, float b) { f32v2_t v = {a, b}; bf16v2_t r = __builtin_convertvector(v, bf16v2_t); return __builtin_bit_cast(unsigned, r); }
; DI void norm_phase(const Params& p, int l, int mode, int B, int G, char* smem) {
;     ...
;   for (int row = B * 8 + wid; row < MT; row += G * 8) {
;     float* X = p.out + (size_t)row * 1024;
;     const float* Xr = (mode == 0 && l == 0 && row < MP) ? p.in[0] + (size_t)row * 1024 : X;
;     float4 v[4];
;     float ss = 0.f;
; #pragma unroll
;     for (int i = 0; i < 4; ++i) { { const f32x4 t4 = __builtin_nontemporal_load((const f32x4*)(Xr + i * 256 + lane * 4)); v[i] = float4{t4[0], t4[1], t4[2], t4[3]}; } ss += v[i].x * v[i].x + v[i].y * v[i].y + v[i].z * v[i].z + v[i].w * v[i].w; }
;     ss = wave_sum(ss);
;     const float rs = rsqrtf(ss * (1.f / 1024.f) + EPS);
;     u16* XN = (u16*)(p.ws + O_XN) + (size_t)row * LDK;
; #pragma unroll
;     for (int i = 0; i < 4; ++i) {
;       v[i] = float4{v[i].x * rs * g[i].x, v[i].y * rs * g[i].y, v[i].z * rs * g[i].z, v[i].w * rs * g[i].w};
;       if (mode == 2) *(float4*)(X + i * 256 + lane * 4) = v[i];
;       else *(uint2*)(XN + i * 256 + lane * 4) = uint2{pack2(v[i].x, v[i].y), pack2(v[i].z, v[i].w)};
;     }
;     if (mode == 0) {
;       float ga[16];
; #pragma unroll
;       for (int r = 0; r < 16; ++r) ga[r] = 0.f;
; #pragma unroll
;       for (int i = 0; i < 4; ++i) {
;         const float xv[4] = {v[i].x, v[i].y, v[i].z, v[i].w};
; #pragma unroll
;         for (int e = 0; e < 4; ++e) {
;           asm volatile("" ::: "memory");
; #pragma unroll
;           for (int q = 0; q < 4; ++q) {
;             const float4 w = ((const float4*)wga)[((i * 4 + e) * 4 + q) * 64 + lane];
;             ga[q * 4 + 0] += xv[e] * w.x; ga[q * 4 + 1] += xv[e] * w.y; ga[q * 4 + 2] += xv[e] * w.z; ga[q * 4 + 3] += xv[e] * w.w;
.LBB0_79:
	s_waitcnt vmcnt(0)
	v_mov_b32_e32 v26, v104
	v_mov_b32_e32 v27, v105
	v_mov_b32_e32 v28, v106
	v_mov_b32_e32 v29, v107
	v_mov_b32_e32 v30, v108
	v_mov_b32_e32 v31, v109
	v_mov_b32_e32 v32, v110
	v_mov_b32_e32 v33, v111
	v_mov_b32_e32 v34, v112
	v_mov_b32_e32 v35, v113
	v_mov_b32_e32 v36, v114
	v_mov_b32_e32 v37, v115
	v_mov_b32_e32 v46, v116
	v_mov_b32_e32 v47, v117
	v_mov_b32_e32 v48, v118
	v_mov_b32_e32 v49, v119
	v_readlane_b32 s20, v254, 31
	v_readlane_b32 s10, v254, 33
	v_readlane_b32 s11, v254, 34
	v_add_u32_e32 v120, s20, v0
	s_nop 0
	v_lshl_add_u64 v[122:123], v[22:23], 0, s[10:11]
	v_cmp_ge_i32_e64 s[34:35], s24, v120
	s_nop 1
	v_cndmask_b32_e64 v120, v0, v120, s[34:35]
	v_cndmask_b32_e64 v122, v22, v122, s[34:35]
	v_cndmask_b32_e64 v123, v23, v123, s[34:35]
	v_cmp_gt_i32_e64 s[72:73], s28, v120
	v_readlane_b32 s10, v253, 63
	v_readlane_b32 s11, v254, 0
	s_and_b64 s[72:73], s[6:7], s[72:73]
	v_mov_b32_e32 v121, s93
	v_mov_b32_e32 v124, s11
	v_cndmask_b32_e64 v125, v121, v124, s[72:73]
	v_mov_b32_e32 v121, s92
	v_mov_b32_e32 v124, s10
	v_cndmask_b32_e64 v124, v121, v124, s[72:73]
	v_lshl_add_u64 v[124:125], v[124:125], 0, v[122:123]
	global_load_dwordx4 v[104:107], v[124:125], off nt
	global_load_dwordx4 v[108:111], v[124:125], off offset:1024 nt
	global_load_dwordx4 v[112:115], v[124:125], off offset:2048 nt
	global_load_dwordx4 v[116:119], v[124:125], off offset:3072 nt
	s_waitcnt lgkmcnt(2)
	s_mov_b32 s10, 0xa544000
	v_mov_b32_e32 v50, v27
	v_mov_b32_e32 v51, v31
	v_mov_b32_e32 v38, v26
	v_mov_b32_e32 v39, v30
	v_mov_b32_e32 v58, v35
	v_mov_b32_e32 v59, v47
	v_pk_mul_f32 v[50:51], v[50:51], v[50:51]
	v_mov_b32_e32 v52, v28
	v_mov_b32_e32 v53, v32
	v_mov_b32_e32 v56, v34
	v_mov_b32_e32 v57, v46
	v_pk_mul_f32 v[58:59], v[58:59], v[58:59]
	v_pk_fma_f32 v[38:39], v[38:39], v[38:39], v[50:51]
	v_mov_b32_e32 v54, v29
	v_mov_b32_e32 v55, v33
	s_waitcnt lgkmcnt(1)
	v_mov_b32_e32 v60, v36
	v_mov_b32_e32 v61, v48
	v_pk_fma_f32 v[50:51], v[56:57], v[56:57], v[58:59]
	v_pk_fma_f32 v[38:39], v[52:53], v[52:53], v[38:39]
	s_waitcnt lgkmcnt(0)
	v_mov_b32_e32 v62, v37
	v_mov_b32_e32 v63, v49
	v_pk_fma_f32 v[50:51], v[60:61], v[60:61], v[50:51]
	v_pk_fma_f32 v[38:39], v[54:55], v[54:55], v[38:39]
	v_pk_fma_f32 v[50:51], v[62:63], v[62:63], v[50:51]
	v_add_f32_e32 v1, v38, v39
	v_add_f32_e32 v1, v1, v50
	v_add_f32_e32 v1, v1, v51
	s_nop 1
	v_add_f32_dpp v1, v1, v1 quad_perm:[1,0,3,2] row_mask:0xf bank_mask:0xf
	s_nop 1
	v_add_f32_dpp v1, v1, v1 quad_perm:[2,3,0,1] row_mask:0xf bank_mask:0xf
	s_nop 1
	v_add_f32_dpp v1, v1, v1 row_ror:4 row_mask:0xf bank_mask:0xf
	s_nop 1
	v_add_f32_dpp v1, v1, v1 row_ror:8 row_mask:0xf bank_mask:0xf
	s_nop 0
	v_mov_b32_e32 v50, v1
	s_nop 1
	v_permlane16_swap_b32_e32 v1, v50
	v_add_f32_e32 v1, v1, v50
	v_mov_b32_e32 v50, v1
	s_nop 1
	v_permlane32_swap_b32_e32 v1, v50
	v_add_f32_e32 v1, v1, v50
	v_lshl_add_u64 v[38:39], s[94:95], 0, v[20:21]
	v_fmamk_f32 v1, v1, 0x3a800000, v186
	v_mul_f32_e32 v50, 0x4b800000, v1
	v_cmp_gt_f32_e64 s[72:73], s1, v1
	s_nop 1
	v_cndmask_b32_e64 v1, v1, v50, s[72:73]
	v_rsq_f32_e32 v1, v1
	v_add_co_u32_e64 v50, s[74:75], s10, v38
	v_mul_f32_e32 v38, 0x45800000, v1
	v_cndmask_b32_e64 v38, v1, v38, s[72:73]
	v_pk_mul_f32 v[26:27], v[26:27], v[38:39] op_sel_hi:[1,0]
	v_pk_mul_f32 v[28:29], v[28:29], v[38:39] op_sel_hi:[1,0]
	v_addc_co_u32_e64 v51, s[74:75], 0, v39, s[74:75]
	v_pk_mul_f32 v[30:31], v[30:31], v[38:39] op_sel_hi:[1,0]
	v_pk_mul_f32 v[32:33], v[32:33], v[38:39] op_sel_hi:[1,0]
	v_pk_mul_f32 v[52:53], v[34:35], v[38:39] op_sel_hi:[1,0]
	v_pk_mul_f32 v[54:55], v[36:37], v[38:39] op_sel_hi:[1,0]
	v_pk_mul_f32 v[46:47], v[46:47], v[38:39] op_sel_hi:[1,0]
	v_pk_mul_f32 v[48:49], v[48:49], v[38:39] op_sel_hi:[1,0]
	v_pk_mul_f32 v[102:103], v[4:5], v[26:27]
	v_pk_mul_f32 v[38:39], v[6:7], v[28:29]
	v_pk_mul_f32 v[36:37], v[8:9], v[30:31]
	v_pk_mul_f32 v[34:35], v[10:11], v[32:33]
	v_pk_mul_f32 v[32:33], v[12:13], v[52:53]
	v_pk_mul_f32 v[30:31], v[14:15], v[54:55]
	v_pk_mul_f32 v[28:29], v[16:17], v[46:47]
	v_pk_mul_f32 v[26:27], v[18:19], v[48:49]
	v_cvt_pk_bf16_f32 v46, v102, v103
	v_cvt_pk_bf16_f32 v47, v38, v39
	v_cvt_pk_bf16_f32 v48, v36, v37
	v_cvt_pk_bf16_f32 v49, v34, v35
	v_cvt_pk_bf16_f32 v52, v32, v33
	v_cvt_pk_bf16_f32 v53, v30, v31
	v_cvt_pk_bf16_f32 v54, v28, v29
	v_cvt_pk_bf16_f32 v55, v26, v27
	global_store_dwordx2 v[50:51], v[46:47], off offset:256
	global_store_dwordx2 v[50:51], v[48:49], off offset:768
	global_store_dwordx2 v[50:51], v[52:53], off offset:1280
	global_store_dwordx2 v[50:51], v[54:55], off offset:1792
	ds_read_b128 v[128:131], v45
	ds_read_b128 v[132:135], v45 offset:1024
	ds_read_b128 v[136:139], v45 offset:2048
	ds_read_b128 v[140:143], v45 offset:3072
	ds_read_b128 v[144:147], v45 offset:4096
	ds_read_b128 v[148:151], v45 offset:5120
	ds_read_b128 v[152:155], v45 offset:6144
	ds_read_b128 v[156:159], v45 offset:7168
	s_waitcnt lgkmcnt(7)
	v_pk_mul_f32 v[214:215], v[102:103], v[128:129] op_sel:[0,0] op_sel_hi:[0,1]
	v_pk_mul_f32 v[216:217], v[102:103], v[130:131] op_sel:[0,0] op_sel_hi:[0,1]
	ds_read_b128 v[128:131], v45 offset:8192
	s_waitcnt lgkmcnt(7)
	v_pk_mul_f32 v[218:219], v[102:103], v[132:133] op_sel:[0,0] op_sel_hi:[0,1]
	v_pk_mul_f32 v[220:221], v[102:103], v[134:135] op_sel:[0,0] op_sel_hi:[0,1]
	ds_read_b128 v[132:135], v45 offset:9216
	s_waitcnt lgkmcnt(7)
	v_pk_mul_f32 v[222:223], v[102:103], v[136:137] op_sel:[0,0] op_sel_hi:[0,1]
	v_pk_mul_f32 v[224:225], v[102:103], v[138:139] op_sel:[0,0] op_sel_hi:[0,1]
	ds_read_b128 v[136:139], v45 offset:10240
	s_waitcnt lgkmcnt(7)
; DI void norm_phase(const Params& p, int l, int mode, int B, int G, char* smem) {
;     ...
;       for (int i = 0; i < 4; ++i) {
;         const float xv[4] = {v[i].x, v[i].y, v[i].z, v[i].w};
; #pragma unroll
;         for (int e = 0; e < 4; ++e) {
;           asm volatile("" ::: "memory");
; #pragma unroll
;           for (int q = 0; q < 4; ++q) {
;             const float4 w = ((const float4*)wga)[((i * 4 + e) * 4 + q) * 64 + lane];
;             ga[q * 4 + 0] += xv[e] * w.x; ga[q * 4 + 1] += xv[e] * w.y; ga[q * 4 + 2] += xv[e] * w.z; ga[q * 4 + 3] += xv[e] * w.w;
;           }
;         }
;       }
	v_pk_mul_f32 v[226:227], v[102:103], v[140:141] op_sel:[0,0] op_sel_hi:[0,1]
	v_pk_mul_f32 v[228:229], v[102:103], v[142:143] op_sel:[0,0] op_sel_hi:[0,1]
	ds_read_b128 v[140:143], v45 offset:11264
	s_waitcnt lgkmcnt(7)
	v_pk_fma_f32 v[214:215], v[102:103], v[144:145], v[214:215] op_sel:[1,0,0] op_sel_hi:[1,1,1]
	v_pk_fma_f32 v[216:217], v[102:103], v[146:147], v[216:217] op_sel:[1,0,0] op_sel_hi:[1,1,1]
	ds_read_b128 v[144:147], v45 offset:12288
	s_waitcnt lgkmcnt(7)
	v_pk_fma_f32 v[218:219], v[102:103], v[148:149], v[218:219] op_sel:[1,0,0] op_sel_hi:[1,1,1]
	v_pk_fma_f32 v[220:221], v[102:103], v[150:151], v[220:221] op_sel:[1,0,0] op_sel_hi:[1,1,1]
	ds_read_b128 v[148:151], v45 offset:13312
	s_waitcnt lgkmcnt(7)
	v_pk_fma_f32 v[222:223], v[102:103], v[152:153], v[222:223] op_sel:[1,0,0] op_sel_hi:[1,1,1]
	v_pk_fma_f32 v[224:225], v[102:103], v[154:155], v[224:225] op_sel:[1,0,0] op_sel_hi:[1,1,1]
	ds_read_b128 v[152:155], v45 offset:14336
	s_waitcnt lgkmcnt(7)
	v_pk_fma_f32 v[226:227], v[102:103], v[156:157], v[226:227] op_sel:[1,0,0] op_sel_hi:[1,1,1]
	v_pk_fma_f32 v[228:229], v[102:103], v[158:159], v[228:229] op_sel:[1,0,0] op_sel_hi:[1,1,1]
	ds_read_b128 v[156:159], v45 offset:15360
	s_waitcnt lgkmcnt(7)
	v_pk_fma_f32 v[214:215], v[38:39], v[128:129], v[214:215] op_sel:[0,0,0] op_sel_hi:[0,1,1]
	v_pk_fma_f32 v[216:217], v[38:39], v[130:131], v[216:217] op_sel:[0,0,0] op_sel_hi:[0,1,1]
	ds_read_b128 v[128:131], v45 offset:16384
	s_waitcnt lgkmcnt(7)
	v_pk_fma_f32 v[218:219], v[38:39], v[132:133], v[218:219] op_sel:[0,0,0] op_sel_hi:[0,1,1]
	v_pk_fma_f32 v[220:221], v[38:39], v[134:135], v[220:221] op_sel:[0,0,0] op_sel_hi:[0,1,1]
	ds_read_b128 v[132:135], v45 offset:17408
	s_waitcnt lgkmcnt(7)
	v_pk_fma_f32 v[222:223], v[38:39], v[136:137], v[222:223] op_sel:[0,0,0] op_sel_hi:[0,1,1]
	v_pk_fma_f32 v[224:225], v[38:39], v[138:139], v[224:225] op_sel:[0,0,0] op_sel_hi:[0,1,1]
	ds_read_b128 v[136:139], v45 offset:18432
	s_waitcnt lgkmcnt(7)
	v_pk_fma_f32 v[226:227], v[38:39], v[140:141], v[226:227] op_sel:[0,0,0] op_sel_hi:[0,1,1]
	v_pk_fma_f32 v[228:229], v[38:39], v[142:143], v[228:229] op_sel:[0,0,0] op_sel_hi:[0,1,1]
	ds_read_b128 v[140:143], v45 offset:19456
	s_waitcnt lgkmcnt(7)
	v_pk_fma_f32 v[214:215], v[38:39], v[144:145], v[214:215] op_sel:[1,0,0] op_sel_hi:[1,1,1]
	v_pk_fma_f32 v[216:217], v[38:39], v[146:147], v[216:217] op_sel:[1,0,0] op_sel_hi:[1,1,1]
	ds_read_b128 v[144:147], v45 offset:20480
	s_waitcnt lgkmcnt(7)
	v_pk_fma_f32 v[218:219], v[38:39], v[148:149], v[218:219] op_sel:[1,0,0] op_sel_hi:[1,1,1]
	v_pk_fma_f32 v[220:221], v[38:39], v[150:151], v[220:221] op_sel:[1,0,0] op_sel_hi:[1,1,1]
	ds_read_b128 v[148:151], v45 offset:21504
	s_waitcnt lgkmcnt(7)
	v_pk_fma_f32 v[222:223], v[38:39], v[152:153], v[222:223] op_sel:[1,0,0] op_sel_hi:[1,1,1]
	v_pk_fma_f32 v[224:225], v[38:39], v[154:155], v[224:225] op_sel:[1,0,0] op_sel_hi:[1,1,1]
	ds_read_b128 v[152:155], v45 offset:22528
	s_waitcnt lgkmcnt(7)
	v_pk_fma_f32 v[226:227], v[38:39], v[156:157], v[226:227] op_sel:[1,0,0] op_sel_hi:[1,1,1]
	v_pk_fma_f32 v[228:229], v[38:39], v[158:159], v[228:229] op_sel:[1,0,0] op_sel_hi:[1,1,1]
	ds_read_b128 v[156:159], v45 offset:23552
	s_waitcnt lgkmcnt(7)
	v_pk_fma_f32 v[214:215], v[36:37], v[128:129], v[214:215] op_sel:[0,0,0] op_sel_hi:[0,1,1]
	v_pk_fma_f32 v[216:217], v[36:37], v[130:131], v[216:217] op_sel:[0,0,0] op_sel_hi:[0,1,1]
	ds_read_b128 v[128:131], v45 offset:24576
	s_waitcnt lgkmcnt(7)
	v_pk_fma_f32 v[218:219], v[36:37], v[132:133], v[218:219] op_sel:[0,0,0] op_sel_hi:[0,1,1]
	v_pk_fma_f32 v[220:221], v[36:37], v[134:135], v[220:221] op_sel:[0,0,0] op_sel_hi:[0,1,1]
	ds_read_b128 v[132:135], v45 offset:25600
	s_waitcnt lgkmcnt(7)
	v_pk_fma_f32 v[222:223], v[36:37], v[136:137], v[222:223] op_sel:[0,0,0] op_sel_hi:[0,1,1]
	v_pk_fma_f32 v[224:225], v[36:37], v[138:139], v[224:225] op_sel:[0,0,0] op_sel_hi:[0,1,1]
	ds_read_b128 v[136:139], v45 offset:26624
	s_waitcnt lgkmcnt(7)
	v_pk_fma_f32 v[226:227], v[36:37], v[140:141], v[226:227] op_sel:[0,0,0] op_sel_hi:[0,1,1]
	v_pk_fma_f32 v[228:229], v[36:37], v[142:143], v[228:229] op_sel:[0,0,0] op_sel_hi:[0,1,1]
	ds_read_b128 v[140:143], v45 offset:27648
	s_waitcnt lgkmcnt(7)
	v_pk_fma_f32 v[214:215], v[36:37], v[144:145], v[214:215] op_sel:[1,0,0] op_sel_hi:[1,1,1]
	v_pk_fma_f32 v[216:217], v[36:37], v[146:147], v[216:217] op_sel:[1,0,0] op_sel_hi:[1,1,1]
	ds_read_b128 v[144:147], v45 offset:28672
	s_waitcnt lgkmcnt(7)
	v_pk_fma_f32 v[218:219], v[36:37], v[148:149], v[218:219] op_sel:[1,0,0] op_sel_hi:[1,1,1]
	v_pk_fma_f32 v[220:221], v[36:37], v[150:151], v[220:221] op_sel:[1,0,0] op_sel_hi:[1,1,1]
	ds_read_b128 v[148:151], v45 offset:29696
	s_waitcnt lgkmcnt(7)
	v_pk_fma_f32 v[222:223], v[36:37], v[152:153], v[222:223] op_sel:[1,0,0] op_sel_hi:[1,1,1]
	v_pk_fma_f32 v[224:225], v[36:37], v[154:155], v[224:225] op_sel:[1,0,0] op_sel_hi:[1,1,1]
	ds_read_b128 v[152:155], v45 offset:30720
	s_waitcnt lgkmcnt(7)
	v_pk_fma_f32 v[226:227], v[36:37], v[156:157], v[226:227] op_sel:[1,0,0] op_sel_hi:[1,1,1]
	v_pk_fma_f32 v[228:229], v[36:37], v[158:159], v[228:229] op_sel:[1,0,0] op_sel_hi:[1,1,1]
	ds_read_b128 v[156:159], v45 offset:31744
	s_waitcnt lgkmcnt(7)
	v_pk_fma_f32 v[214:215], v[34:35], v[128:129], v[214:215] op_sel:[0,0,0] op_sel_hi:[0,1,1]
	v_pk_fma_f32 v[216:217], v[34:35], v[130:131], v[216:217] op_sel:[0,0,0] op_sel_hi:[0,1,1]
	ds_read_b128 v[128:131], v45 offset:32768
	s_waitcnt lgkmcnt(7)
	v_pk_fma_f32 v[218:219], v[34:35], v[132:133], v[218:219] op_sel:[0,0,0] op_sel_hi:[0,1,1]
	v_pk_fma_f32 v[220:221], v[34:35], v[134:135], v[220:221] op_sel:[0,0,0] op_sel_hi:[0,1,1]
	ds_read_b128 v[132:135], v45 offset:33792
	s_waitcnt lgkmcnt(7)
; DI void norm_phase(const Params& p, int l, int mode, int B, int G, char* smem) {
;     ...
;       for (int i = 0; i < 4; ++i) {
;         const float xv[4] = {v[i].x, v[i].y, v[i].z, v[i].w};
; #pragma unroll
;         for (int e = 0; e < 4; ++e) {
;           asm volatile("" ::: "memory");
; #pragma unroll
;           for (int q = 0; q < 4; ++q) {
;             const float4 w = ((const float4*)wga)[((i * 4 + e) * 4 + q) * 64 + lane];
;             ga[q * 4 + 0] += xv[e] * w.x; ga[q * 4 + 1] += xv[e] * w.y; ga[q * 4 + 2] += xv[e] * w.z; ga[q * 4 + 3] += xv[e] * w.w;
;           }
;         }
;       }
	v_pk_fma_f32 v[222:223], v[34:35], v[136:137], v[222:223] op_sel:[0,0,0] op_sel_hi:[0,1,1]
	v_pk_fma_f32 v[224:225], v[34:35], v[138:139], v[224:225] op_sel:[0,0,0] op_sel_hi:[0,1,1]
	ds_read_b128 v[136:139], v45 offset:34816
	s_waitcnt lgkmcnt(7)
	v_pk_fma_f32 v[226:227], v[34:35], v[140:141], v[226:227] op_sel:[0,0,0] op_sel_hi:[0,1,1]
	v_pk_fma_f32 v[228:229], v[34:35], v[142:143], v[228:229] op_sel:[0,0,0] op_sel_hi:[0,1,1]
	ds_read_b128 v[140:143], v45 offset:35840
	s_waitcnt lgkmcnt(7)
	v_pk_fma_f32 v[214:215], v[34:35], v[144:145], v[214:215] op_sel:[1,0,0] op_sel_hi:[1,1,1]
	v_pk_fma_f32 v[216:217], v[34:35], v[146:147], v[216:217] op_sel:[1,0,0] op_sel_hi:[1,1,1]
	ds_read_b128 v[144:147], v45 offset:36864
	s_waitcnt lgkmcnt(7)
	v_pk_fma_f32 v[218:219], v[34:35], v[148:149], v[218:219] op_sel:[1,0,0] op_sel_hi:[1,1,1]
	v_pk_fma_f32 v[220:221], v[34:35], v[150:151], v[220:221] op_sel:[1,0,0] op_sel_hi:[1,1,1]
	ds_read_b128 v[148:151], v45 offset:37888
	s_waitcnt lgkmcnt(7)
	v_pk_fma_f32 v[222:223], v[34:35], v[152:153], v[222:223] op_sel:[1,0,0] op_sel_hi:[1,1,1]
	v_pk_fma_f32 v[224:225], v[34:35], v[154:155], v[224:225] op_sel:[1,0,0] op_sel_hi:[1,1,1]
	ds_read_b128 v[152:155], v45 offset:38912
	s_waitcnt lgkmcnt(7)
	v_pk_fma_f32 v[226:227], v[34:35], v[156:157], v[226:227] op_sel:[1,0,0] op_sel_hi:[1,1,1]
	v_pk_fma_f32 v[228:229], v[34:35], v[158:159], v[228:229] op_sel:[1,0,0] op_sel_hi:[1,1,1]
	ds_read_b128 v[156:159], v45 offset:39936
	s_waitcnt lgkmcnt(7)
	v_pk_fma_f32 v[214:215], v[32:33], v[128:129], v[214:215] op_sel:[0,0,0] op_sel_hi:[0,1,1]
	v_pk_fma_f32 v[216:217], v[32:33], v[130:131], v[216:217] op_sel:[0,0,0] op_sel_hi:[0,1,1]
	ds_read_b128 v[128:131], v45 offset:40960
	s_waitcnt lgkmcnt(7)
	v_pk_fma_f32 v[218:219], v[32:33], v[132:133], v[218:219] op_sel:[0,0,0] op_sel_hi:[0,1,1]
	v_pk_fma_f32 v[220:221], v[32:33], v[134:135], v[220:221] op_sel:[0,0,0] op_sel_hi:[0,1,1]
	ds_read_b128 v[132:135], v45 offset:41984
	s_waitcnt lgkmcnt(7)
	v_pk_fma_f32 v[222:223], v[32:33], v[136:137], v[222:223] op_sel:[0,0,0] op_sel_hi:[0,1,1]
	v_pk_fma_f32 v[224:225], v[32:33], v[138:139], v[224:225] op_sel:[0,0,0] op_sel_hi:[0,1,1]
	ds_read_b128 v[136:139], v45 offset:43008
	s_waitcnt lgkmcnt(7)
	v_pk_fma_f32 v[226:227], v[32:33], v[140:141], v[226:227] op_sel:[0,0,0] op_sel_hi:[0,1,1]
	v_pk_fma_f32 v[228:229], v[32:33], v[142:143], v[228:229] op_sel:[0,0,0] op_sel_hi:[0,1,1]
	ds_read_b128 v[140:143], v45 offset:44032
	s_waitcnt lgkmcnt(7)
	v_pk_fma_f32 v[214:215], v[32:33], v[144:145], v[214:215] op_sel:[1,0,0] op_sel_hi:[1,1,1]
	v_pk_fma_f32 v[216:217], v[32:33], v[146:147], v[216:217] op_sel:[1,0,0] op_sel_hi:[1,1,1]
	ds_read_b128 v[144:147], v45 offset:45056
	s_waitcnt lgkmcnt(7)
	v_pk_fma_f32 v[218:219], v[32:33], v[148:149], v[218:219] op_sel:[1,0,0] op_sel_hi:[1,1,1]
	v_pk_fma_f32 v[220:221], v[32:33], v[150:151], v[220:221] op_sel:[1,0,0] op_sel_hi:[1,1,1]
	ds_read_b128 v[148:151], v45 offset:46080
	s_waitcnt lgkmcnt(7)
	v_pk_fma_f32 v[222:223], v[32:33], v[152:153], v[222:223] op_sel:[1,0,0] op_sel_hi:[1,1,1]
	v_pk_fma_f32 v[224:225], v[32:33], v[154:155], v[224:225] op_sel:[1,0,0] op_sel_hi:[1,1,1]
	ds_read_b128 v[152:155], v45 offset:47104
	s_waitcnt lgkmcnt(7)
	v_pk_fma_f32 v[226:227], v[32:33], v[156:157], v[226:227] op_sel:[1,0,0] op_sel_hi:[1,1,1]
	v_pk_fma_f32 v[228:229], v[32:33], v[158:159], v[228:229] op_sel:[1,0,0] op_sel_hi:[1,1,1]
	ds_read_b128 v[156:159], v45 offset:48128
	s_waitcnt lgkmcnt(7)
	v_pk_fma_f32 v[214:215], v[30:31], v[128:129], v[214:215] op_sel:[0,0,0] op_sel_hi:[0,1,1]
	v_pk_fma_f32 v[216:217], v[30:31], v[130:131], v[216:217] op_sel:[0,0,0] op_sel_hi:[0,1,1]
	ds_read_b128 v[128:131], v45 offset:49152
	s_waitcnt lgkmcnt(7)
	v_pk_fma_f32 v[218:219], v[30:31], v[132:133], v[218:219] op_sel:[0,0,0] op_sel_hi:[0,1,1]
	v_pk_fma_f32 v[220:221], v[30:31], v[134:135], v[220:221] op_sel:[0,0,0] op_sel_hi:[0,1,1]
	ds_read_b128 v[132:135], v45 offset:50176
	s_waitcnt lgkmcnt(7)
	v_pk_fma_f32 v[222:223], v[30:31], v[136:137], v[222:223] op_sel:[0,0,0] op_sel_hi:[0,1,1]
	v_pk_fma_f32 v[224:225], v[30:31], v[138:139], v[224:225] op_sel:[0,0,0] op_sel_hi:[0,1,1]
	ds_read_b128 v[136:139], v45 offset:51200
	s_waitcnt lgkmcnt(7)
	v_pk_fma_f32 v[226:227], v[30:31], v[140:141], v[226:227] op_sel:[0,0,0] op_sel_hi:[0,1,1]
	v_pk_fma_f32 v[228:229], v[30:31], v[142:143], v[228:229] op_sel:[0,0,0] op_sel_hi:[0,1,1]
	ds_read_b128 v[140:143], v45 offset:52224
	s_waitcnt lgkmcnt(7)
	v_pk_fma_f32 v[214:215], v[30:31], v[144:145], v[214:215] op_sel:[1,0,0] op_sel_hi:[1,1,1]
	v_pk_fma_f32 v[216:217], v[30:31], v[146:147], v[216:217] op_sel:[1,0,0] op_sel_hi:[1,1,1]
	ds_read_b128 v[144:147], v45 offset:53248
	s_waitcnt lgkmcnt(7)
	v_pk_fma_f32 v[218:219], v[30:31], v[148:149], v[218:219] op_sel:[1,0,0] op_sel_hi:[1,1,1]
	v_pk_fma_f32 v[220:221], v[30:31], v[150:151], v[220:221] op_sel:[1,0,0] op_sel_hi:[1,1,1]
	ds_read_b128 v[148:151], v45 offset:54272
	s_waitcnt lgkmcnt(7)
	v_pk_fma_f32 v[222:223], v[30:31], v[152:153], v[222:223] op_sel:[1,0,0] op_sel_hi:[1,1,1]
	v_pk_fma_f32 v[224:225], v[30:31], v[154:155], v[224:225] op_sel:[1,0,0] op_sel_hi:[1,1,1]
	ds_read_b128 v[152:155], v45 offset:55296
	s_waitcnt lgkmcnt(7)
	v_pk_fma_f32 v[226:227], v[30:31], v[156:157], v[226:227] op_sel:[1,0,0] op_sel_hi:[1,1,1]
	v_pk_fma_f32 v[228:229], v[30:31], v[158:159], v[228:229] op_sel:[1,0,0] op_sel_hi:[1,1,1]
	ds_read_b128 v[156:159], v45 offset:56320
	s_waitcnt lgkmcnt(7)
; DI void norm_phase(const Params& p, int l, int mode, int B, int G, char* smem) {
;     ...
;           for (int q = 0; q < 4; ++q) {
;             const float4 w = ((const float4*)wga)[((i * 4 + e) * 4 + q) * 64 + lane];
;             ga[q * 4 + 0] += xv[e] * w.x; ga[q * 4 + 1] += xv[e] * w.y; ga[q * 4 + 2] += xv[e] * w.z; ga[q * 4 + 3] += xv[e] * w.w;
;           }
;         }
;       }
;       float mine = 0.f;
; #pragma unroll
;       for (int r = 0; r < 16; ++r) { const float s = wave_sum(ga[r]); if (lane == r) mine = s; }
;       if (lane < 16) ((float*)(p.ws + O_GA))[(size_t)row * 16 + lane] = mine;
	v_pk_fma_f32 v[214:215], v[28:29], v[128:129], v[214:215] op_sel:[0,0,0] op_sel_hi:[0,1,1]
	v_pk_fma_f32 v[216:217], v[28:29], v[130:131], v[216:217] op_sel:[0,0,0] op_sel_hi:[0,1,1]
	ds_read_b128 v[128:131], v45 offset:57344
	s_waitcnt lgkmcnt(7)
	v_pk_fma_f32 v[218:219], v[28:29], v[132:133], v[218:219] op_sel:[0,0,0] op_sel_hi:[0,1,1]
	v_pk_fma_f32 v[220:221], v[28:29], v[134:135], v[220:221] op_sel:[0,0,0] op_sel_hi:[0,1,1]
	ds_read_b128 v[132:135], v45 offset:58368
	s_waitcnt lgkmcnt(7)
	v_pk_fma_f32 v[222:223], v[28:29], v[136:137], v[222:223] op_sel:[0,0,0] op_sel_hi:[0,1,1]
	v_pk_fma_f32 v[224:225], v[28:29], v[138:139], v[224:225] op_sel:[0,0,0] op_sel_hi:[0,1,1]
	ds_read_b128 v[136:139], v45 offset:59392
	s_waitcnt lgkmcnt(7)
	v_pk_fma_f32 v[226:227], v[28:29], v[140:141], v[226:227] op_sel:[0,0,0] op_sel_hi:[0,1,1]
	v_pk_fma_f32 v[228:229], v[28:29], v[142:143], v[228:229] op_sel:[0,0,0] op_sel_hi:[0,1,1]
	ds_read_b128 v[140:143], v45 offset:60416
	s_waitcnt lgkmcnt(7)
	v_pk_fma_f32 v[214:215], v[28:29], v[144:145], v[214:215] op_sel:[1,0,0] op_sel_hi:[1,1,1]
	v_pk_fma_f32 v[216:217], v[28:29], v[146:147], v[216:217] op_sel:[1,0,0] op_sel_hi:[1,1,1]
	ds_read_b128 v[144:147], v45 offset:61440
	s_waitcnt lgkmcnt(7)
	v_pk_fma_f32 v[218:219], v[28:29], v[148:149], v[218:219] op_sel:[1,0,0] op_sel_hi:[1,1,1]
	v_pk_fma_f32 v[220:221], v[28:29], v[150:151], v[220:221] op_sel:[1,0,0] op_sel_hi:[1,1,1]
	ds_read_b128 v[148:151], v45 offset:62464
	s_waitcnt lgkmcnt(7)
	v_pk_fma_f32 v[222:223], v[28:29], v[152:153], v[222:223] op_sel:[1,0,0] op_sel_hi:[1,1,1]
	v_pk_fma_f32 v[224:225], v[28:29], v[154:155], v[224:225] op_sel:[1,0,0] op_sel_hi:[1,1,1]
	ds_read_b128 v[152:155], v45 offset:63488
	s_waitcnt lgkmcnt(7)
	v_pk_fma_f32 v[226:227], v[28:29], v[156:157], v[226:227] op_sel:[1,0,0] op_sel_hi:[1,1,1]
	v_pk_fma_f32 v[228:229], v[28:29], v[158:159], v[228:229] op_sel:[1,0,0] op_sel_hi:[1,1,1]
	ds_read_b128 v[156:159], v45 offset:64512
	s_waitcnt lgkmcnt(7)
	v_pk_fma_f32 v[214:215], v[26:27], v[128:129], v[214:215] op_sel:[0,0,0] op_sel_hi:[0,1,1]
	v_pk_fma_f32 v[216:217], v[26:27], v[130:131], v[216:217] op_sel:[0,0,0] op_sel_hi:[0,1,1]
	s_waitcnt lgkmcnt(6)
	v_pk_fma_f32 v[218:219], v[26:27], v[132:133], v[218:219] op_sel:[0,0,0] op_sel_hi:[0,1,1]
	v_pk_fma_f32 v[220:221], v[26:27], v[134:135], v[220:221] op_sel:[0,0,0] op_sel_hi:[0,1,1]
	s_waitcnt lgkmcnt(5)
	v_pk_fma_f32 v[222:223], v[26:27], v[136:137], v[222:223] op_sel:[0,0,0] op_sel_hi:[0,1,1]
	v_pk_fma_f32 v[224:225], v[26:27], v[138:139], v[224:225] op_sel:[0,0,0] op_sel_hi:[0,1,1]
	s_waitcnt lgkmcnt(4)
	v_pk_fma_f32 v[226:227], v[26:27], v[140:141], v[226:227] op_sel:[0,0,0] op_sel_hi:[0,1,1]
	v_pk_fma_f32 v[228:229], v[26:27], v[142:143], v[228:229] op_sel:[0,0,0] op_sel_hi:[0,1,1]
	s_waitcnt lgkmcnt(3)
	v_pk_fma_f32 v[214:215], v[26:27], v[144:145], v[214:215] op_sel:[1,0,0] op_sel_hi:[1,1,1]
	v_pk_fma_f32 v[216:217], v[26:27], v[146:147], v[216:217] op_sel:[1,0,0] op_sel_hi:[1,1,1]
	s_waitcnt lgkmcnt(2)
	v_pk_fma_f32 v[218:219], v[26:27], v[148:149], v[218:219] op_sel:[1,0,0] op_sel_hi:[1,1,1]
	v_pk_fma_f32 v[220:221], v[26:27], v[150:151], v[220:221] op_sel:[1,0,0] op_sel_hi:[1,1,1]
	s_waitcnt lgkmcnt(1)
	v_pk_fma_f32 v[222:223], v[26:27], v[152:153], v[222:223] op_sel:[1,0,0] op_sel_hi:[1,1,1]
	v_pk_fma_f32 v[224:225], v[26:27], v[154:155], v[224:225] op_sel:[1,0,0] op_sel_hi:[1,1,1]
	s_waitcnt lgkmcnt(0)
	v_pk_fma_f32 v[226:227], v[26:27], v[156:157], v[226:227] op_sel:[1,0,0] op_sel_hi:[1,1,1]
	v_pk_fma_f32 v[228:229], v[26:27], v[158:159], v[228:229] op_sel:[1,0,0] op_sel_hi:[1,1,1]
	s_mov_b32 s34, 0xaaaaaaaa
	s_mov_b32 s35, 0xaaaaaaaa
	s_mov_b32 s72, 0xcccccccc
	s_mov_b32 s73, 0xcccccccc
	v_permlane32_swap_b32_e32 v214, v222
	v_permlane32_swap_b32_e32 v215, v223
	v_permlane32_swap_b32_e32 v216, v224
	v_permlane32_swap_b32_e32 v217, v225
	v_permlane32_swap_b32_e32 v218, v226
	v_permlane32_swap_b32_e32 v219, v227
	v_permlane32_swap_b32_e32 v220, v228
	v_permlane32_swap_b32_e32 v221, v229
	v_add_f32_e32 v214, v214, v222
	v_add_f32_e32 v215, v215, v223
	v_add_f32_e32 v216, v216, v224
	v_add_f32_e32 v217, v217, v225
	v_add_f32_e32 v218, v218, v226
	v_add_f32_e32 v219, v219, v227
	v_add_f32_e32 v220, v220, v228
	v_add_f32_e32 v221, v221, v229
	v_permlane16_swap_b32_e32 v214, v218
	v_permlane16_swap_b32_e32 v215, v219
	v_permlane16_swap_b32_e32 v216, v220
	v_permlane16_swap_b32_e32 v217, v221
	v_add_f32_e32 v214, v214, v218
	v_add_f32_e32 v215, v215, v219
	v_add_f32_e32 v216, v216, v220
	v_add_f32_e32 v217, v217, v221
	v_add_f32_dpp v230, v214, v214 quad_perm:[1,0,3,2] row_mask:0xf bank_mask:0xf
	v_add_f32_dpp v231, v215, v215 quad_perm:[1,0,3,2] row_mask:0xf bank_mask:0xf
	v_add_f32_dpp v232, v216, v216 quad_perm:[1,0,3,2] row_mask:0xf bank_mask:0xf
	v_add_f32_dpp v233, v217, v217 quad_perm:[1,0,3,2] row_mask:0xf bank_mask:0xf
	v_cndmask_b32_e64 v234, v230, v231, s[34:35]
	v_cndmask_b32_e64 v235, v232, v233, s[34:35]
	s_nop 1
	v_add_f32_dpp v236, v234, v234 quad_perm:[2,3,0,1] row_mask:0xf bank_mask:0xf
	v_add_f32_dpp v237, v235, v235 quad_perm:[2,3,0,1] row_mask:0xf bank_mask:0xf
	v_and_b32_e32 v239, 3, v190
	v_lshlrev_b32_e32 v240, 2, v190
	v_cndmask_b32_e64 v238, v236, v237, s[72:73]
	v_and_b32_e32 v240, 0x30, v240
	v_or_b32_e32 v239, v239, v240
	v_add_f32_dpp v238, v238, v238 row_ror:4 row_mask:0xf bank_mask:0xf
	v_lshlrev_b32_e32 v239, 2, v239
	s_nop 1
	v_add_f32_dpp v238, v238, v238 row_ror:8 row_mask:0xf bank_mask:0xf
	s_nop 0
	ds_bpermute_b32 v1, v239, v238
	s_waitcnt lgkmcnt(0)
	s_and_saveexec_b64 s[12:13], vcc
	s_cbranch_execz .LBB0_78
	v_lshl_add_u64 v[26:27], s[94:95], 0, v[24:25]
	global_store_dword v[26:27], v1, off
	s_branch .LBB0_78

; DI int TID() { int t = threadIdx.x & 255; asm volatile("" : "+v"(t)); return t; }
; DI void gla_bcum(const Params& p, int l, int row0, int Lc, int h, float* bc, float* tot, float* gas) {
;   const int tid = TID(), kd = tid & 63, tq = tid >> 6;
;   const float* W2 = p.in[12] + (size_t)l * 16 * 256 + h * 64 + kd;
;   const float b2 = p.in[13][(size_t)l * 256 + h * 64 + kd];
;   const float* GA = (const float*)(p.ws + O_GA);
;   {
;     const int r = tid >> 2, part = tid & 3;
;     float4 v = {0.f, 0.f, 0.f, 0.f};
;     if (r < Lc) v = *(const float4*)(GA + (size_t)(row0 + r) * 16 + part * 4);
;     *(float4*)(gas + r * 16 + part * 4) = v;
;   }
;   float w[16];
; #pragma unroll
;   for (int r = 0; r < 16; ++r) w[r] = W2[r * 256];
;   __syncthreads();
.LBB0_1393:
	s_movk_i32 s10, 0x7ff
	v_mov_b32_e32 v2, v184
	v_cmp_lt_i32_e32 vcc, s10, v0
	s_and_saveexec_b64 s[10:11], vcc
	s_xor_b64 s[10:11], exec, s[10:11]
	v_add_u32_e32 v1, 0xfffff800, v0
	v_lshrrev_b32_e32 v1, 2, v1
	s_or_saveexec_b64 s[26:27], s[10:11]
	v_mov_b32_e32 v16, 32
	v_mov_b32_e32 v4, 0x8000
	v_mov_b32_e32 v5, 5
	v_mov_b32_e32 v6, v0
	s_xor_b64 exec, exec, s[26:27]
	v_lshlrev_b32_e32 v4, 4, v0
	v_and_b32_e32 v1, 0x7f, v0
	v_lshrrev_b32_e32 v6, 7, v0
	v_and_b32_e32 v4, 0xffffe000, v4
	v_mov_b32_e32 v16, 64
	v_mov_b32_e32 v5, 6
	s_or_b64 exec, exec, s[26:27]
	v_and_b32_e32 v10, 3, v6
	v_mov_b32_e32 v20, v185
	v_mov_b32_e32 v14, v185
	s_waitcnt vmcnt(0) lgkmcnt(0)
	s_barrier
	v_lshlrev_b32_e32 v172, 8, v10
	v_and_b32_e32 v8, 63, v14
	v_lshl_add_u64 v[6:7], s[8:9], 0, v[172:173]
	v_lshlrev_b32_e32 v8, 2, v8
	v_mov_b32_e32 v9, v173
	v_lshl_add_u64 v[6:7], v[6:7], 0, v[8:9]
	global_load_dword v18, v[6:7], off
	v_ashrrev_i32_e32 v11, 2, v14
	v_and_b32_e32 v9, 3, v14
	v_cmp_ge_i32_e32 vcc, v11, v16
	v_lshlrev_b32_e32 v12, 2, v9
	s_and_saveexec_b64 s[10:11], vcc
	s_xor_b64 s[10:11], exec, s[10:11]
	v_lshlrev_b32_e32 v12, 2, v9
	s_or_saveexec_b64 s[26:27], s[10:11]
	v_lshl_add_u32 v17, v1, v5, v4
	v_mov_b32_e32 v30, 0
	v_mov_b32_e32 v100, 0
	v_mov_b32_e32 v101, 0
	v_mov_b32_e32 v102, 0
	v_mov_b32_e32 v103, 0
	s_xor_b64 exec, exec, s[26:27]
	s_cbranch_execz .LBB0_1401
	v_add_u32_e32 v4, v11, v17
	v_ashrrev_i32_e32 v5, 31, v4
	v_readlane_b32 s10, v251, 13
	v_lshlrev_b64 v[4:5], 6, v[4:5]
	v_readlane_b32 s11, v251, 14
	v_lshlrev_b32_e32 v6, 4, v9
	v_mov_b32_e32 v7, v173
	v_lshl_add_u64 v[4:5], s[10:11], 0, v[4:5]
	v_lshl_add_u64 v[4:5], v[4:5], 0, v[6:7]
	global_load_dwordx4 v[100:103], v[4:5], off
.LBB0_1401:
	s_or_b64 exec, exec, s[26:27]
	v_lshlrev_b32_e32 v1, 6, v10
	v_lshlrev_b32_e32 v22, 2, v1
	v_mov_b32_e32 v23, v173
	v_lshl_add_u64 v[22:23], s[6:7], 0, v[22:23]
	v_mov_b32_e32 v9, v173
	v_lshl_add_u64 v[28:29], v[22:23], 0, v[8:9]
	v_lshrrev_b32_e32 v9, 8, v2
	s_mov_b32 s10, 0x12000
	v_mad_i32_i24 v2, v9, s10, 16
	v_lshlrev_b32_e32 v10, 6, v11
	v_lshlrev_b32_e32 v11, 2, v12
	v_add3_u32 v10, v2, v10, v11
	v_mov_b32_e32 v104, v10
	v_add_co_u32_e32 v4, vcc, 0x1000, v28
	global_load_dword v19, v[28:29], off
	global_load_dword v21, v[28:29], off offset:1024
	global_load_dword v22, v[28:29], off offset:2048
	global_load_dword v23, v[28:29], off offset:3072
	v_addc_co_u32_e32 v5, vcc, 0, v29, vcc
	v_add_co_u32_e32 v6, vcc, 0x2000, v28
	global_load_dword v24, v[4:5], off
	global_load_dword v25, v[4:5], off offset:1024
	global_load_dword v26, v[4:5], off offset:2048
	global_load_dword v27, v[4:5], off offset:3072
	v_addc_co_u32_e32 v7, vcc, 0, v29, vcc
	v_add_co_u32_e32 v28, vcc, 0x3000, v28
	global_load_dword v12, v[6:7], off
	global_load_dword v13, v[6:7], off offset:1024
	global_load_dword v4, v[6:7], off offset:2048
	global_load_dword v5, v[6:7], off offset:3072
	v_addc_co_u32_e32 v29, vcc, 0, v29, vcc
	global_load_dword v10, v[28:29], off
	global_load_dword v11, v[28:29], off offset:1024
	global_load_dword v6, v[28:29], off offset:2048
	global_load_dword v7, v[28:29], off offset:3072
	v_ashrrev_i32_e32 v15, 6, v14
	v_lshlrev_b32_e32 v29, 4, v15
	v_cmp_lt_i32_e32 vcc, v29, v16
	s_waitcnt vmcnt(16)
	ds_write_b128 v104, v[100:103] offset:18432
	s_waitcnt lgkmcnt(0)
	s_barrier
	s_and_saveexec_b64 s[26:27], vcc
	s_cbranch_execz .LBB0_1403
	v_lshl_add_u32 v28, v15, 10, v2
	ds_read_b128 v[30:33], v28 offset:18432
	ds_read_b128 v[34:37], v28 offset:18448
	ds_read_b128 v[38:41], v28 offset:18464
	ds_read_b128 v[42:45], v28 offset:18480
	s_mov_b32 s10, 0xbd800000
	s_waitcnt vmcnt(15) lgkmcnt(3)
	v_fma_f32 v28, v19, v30, v18
	s_waitcnt vmcnt(14)
	v_fmac_f32_e32 v28, v21, v31
	s_waitcnt vmcnt(13)
	v_fmac_f32_e32 v28, v22, v32
	s_waitcnt vmcnt(12)
	v_fmac_f32_e32 v28, v23, v33
	s_waitcnt vmcnt(11) lgkmcnt(2)
	v_fmac_f32_e32 v28, v24, v34
	s_waitcnt vmcnt(10)
	v_fmac_f32_e32 v28, v25, v35
	s_waitcnt vmcnt(9)
	v_fmac_f32_e32 v28, v26, v36
	s_waitcnt vmcnt(8)
	v_fmac_f32_e32 v28, v27, v37
	s_waitcnt vmcnt(6) lgkmcnt(1)
	v_pk_mul_f32 v[30:31], v[12:13], v[38:39]
	s_nop 0
	v_add_f32_e32 v28, v28, v30
	v_add_f32_e32 v28, v28, v31
	s_waitcnt vmcnt(4)
	v_pk_mul_f32 v[30:31], v[4:5], v[40:41]
	s_nop 0
	v_add_f32_e32 v28, v28, v30
	v_add_f32_e32 v28, v28, v31
	s_waitcnt vmcnt(2) lgkmcnt(0)
	v_pk_mul_f32 v[30:31], v[10:11], v[42:43]
	s_nop 0
	v_add_f32_e32 v28, v28, v30
	v_add_f32_e32 v28, v28, v31
	s_waitcnt vmcnt(0)
	v_pk_mul_f32 v[30:31], v[6:7], v[44:45]
	s_nop 0
	v_add_f32_e32 v28, v28, v30
	v_add_f32_e32 v28, v28, v31
	v_max_f32_e64 v30, -v28, 0
	v_mul_f32_e64 v28, |v28|, s90
	v_exp_f32_e32 v28, v28
	s_nop 0
	v_add_f32_e32 v28, 1.0, v28
	v_cmp_gt_f32_e32 vcc, s1, v28
	s_nop 1
	v_cndmask_b32_e64 v31, 0, 32, vcc
	v_ldexp_f32 v28, v28, v31
	v_log_f32_e32 v28, v28
	s_nop 0
	v_mul_f32_e32 v31, 0x3f317217, v28
	v_fma_f32 v31, v28, s91, -v31
	v_fmac_f32_e32 v31, 0x3377d1cf, v28
	v_fmac_f32_e32 v31, 0x3f317217, v28
	v_cmp_lt_f32_e64 s[38:39], |v28|, s84
	s_nop 1
	v_cndmask_b32_e64 v28, v28, v31, s[38:39]
	v_cndmask_b32_e32 v31, 0, v213, vcc
	v_sub_f32_e32 v28, v28, v31
	v_add_f32_e32 v28, v30, v28
	v_fma_f32 v30, v28, s10, 0

; DI int TID() { int t = threadIdx.x & 255; asm volatile("" : "+v"(t)); return t; }
; DI void gla_bcum(const Params& p, int l, int row0, int Lc, int h, float* bc, float* tot, float* gas) {
;   const int tid = TID(), kd = tid & 63, tq = tid >> 6;
;   const float* W2 = p.in[12] + (size_t)l * 16 * 256 + h * 64 + kd;
;   const float b2 = p.in[13][(size_t)l * 256 + h * 64 + kd];
;   const float* GA = (const float*)(p.ws + O_GA);
;   {
;     const int r = tid >> 2, part = tid & 3;
;     float4 v = {0.f, 0.f, 0.f, 0.f};
;     if (r < Lc) v = *(const float4*)(GA + (size_t)(row0 + r) * 16 + part * 4);
;     *(float4*)(gas + r * 16 + part * 4) = v;
;   }
;   float w[16];
; #pragma unroll
;   for (int r = 0; r < 16; ++r) w[r] = W2[r * 256];
;   __syncthreads();
.LBB0_1842:
	s_movk_i32 s4, 0x7ff
	v_mov_b32_e32 v10, v184
	v_cmp_lt_i32_e32 vcc, s4, v0
	s_and_saveexec_b64 s[4:5], vcc
	s_xor_b64 s[4:5], exec, s[4:5]
	v_add_u32_e32 v1, 0xfffff800, v0
	v_lshrrev_b32_e32 v1, 2, v1
	s_or_saveexec_b64 s[4:5], s[4:5]
	v_mov_b32_e32 v2, 32
	v_mov_b32_e32 v4, 0x8000
	s_waitcnt lgkmcnt(0)
	v_mov_b32_e32 v5, 5
	v_mov_b32_e32 v6, v0
	s_xor_b64 exec, exec, s[4:5]
	v_lshlrev_b32_e32 v2, 4, v0
	v_and_b32_e32 v1, 0x7f, v0
	v_lshrrev_b32_e32 v6, 7, v0
	v_and_b32_e32 v4, 0xffffe000, v2
	v_mov_b32_e32 v2, 64
	v_mov_b32_e32 v5, 6
	s_or_b64 exec, exec, s[4:5]
	s_waitcnt vmcnt(5)
	v_and_b32_e32 v47, 3, v6
	s_waitcnt vmcnt(4)
	v_mov_b32_e32 v46, v185
	v_mov_b32_e32 v14, v185
	s_barrier
	v_lshlrev_b32_e32 v172, 8, v47
	v_and_b32_e32 v8, 63, v14
	v_lshl_add_u64 v[6:7], s[44:45], 0, v[172:173]
	v_lshlrev_b32_e32 v8, 2, v8
	v_mov_b32_e32 v9, v173
	v_lshl_add_u64 v[6:7], v[6:7], 0, v[8:9]
	global_load_dword v16, v[6:7], off
	v_ashrrev_i32_e32 v11, 2, v14
	v_and_b32_e32 v9, 3, v14
	v_cmp_ge_i32_e32 vcc, v11, v2
	v_lshlrev_b32_e32 v12, 2, v9
	s_and_saveexec_b64 s[4:5], vcc
	s_xor_b64 s[4:5], exec, s[4:5]
	v_lshlrev_b32_e32 v12, 2, v9
	s_or_saveexec_b64 s[4:5], s[4:5]
	v_lshl_add_u32 v44, v1, v5, v4
	v_mov_b32_e32 v27, 0
	v_mov_b32_e32 v100, 0
	v_mov_b32_e32 v101, 0
	v_mov_b32_e32 v102, 0
	v_mov_b32_e32 v103, 0
	s_xor_b64 exec, exec, s[4:5]
	s_cbranch_execz .LBB0_1850
	v_add_u32_e32 v4, v11, v44
	v_ashrrev_i32_e32 v5, 31, v4
	v_readlane_b32 s6, v251, 13
	v_lshlrev_b64 v[4:5], 6, v[4:5]
	v_readlane_b32 s7, v251, 14
	v_lshlrev_b32_e32 v6, 4, v9
	v_mov_b32_e32 v7, v173
	v_lshl_add_u64 v[4:5], s[6:7], 0, v[4:5]
	v_lshl_add_u64 v[4:5], v[4:5], 0, v[6:7]
	global_load_dwordx4 v[100:103], v[4:5], off
.LBB0_1850:
	s_or_b64 exec, exec, s[4:5]
	v_lshlrev_b32_e32 v1, 6, v47
	v_lshlrev_b32_e32 v18, 2, v1
	v_mov_b32_e32 v19, v173
	v_lshl_add_u64 v[18:19], s[42:43], 0, v[18:19]
	v_mov_b32_e32 v9, v173
	v_lshl_add_u64 v[28:29], v[18:19], 0, v[8:9]
	v_lshrrev_b32_e32 v9, 8, v10
	s_mov_b32 s4, 0x12000
	s_waitcnt vmcnt(4)
	v_mad_i32_i24 v45, v9, s4, 16
	v_lshlrev_b32_e32 v10, 6, v11
	v_lshlrev_b32_e32 v11, 2, v12
	v_add3_u32 v10, v45, v10, v11
	v_mov_b32_e32 v104, v10
	v_add_co_u32_e32 v4, vcc, 0x1000, v28
	global_load_dword v17, v[28:29], off
	global_load_dword v18, v[28:29], off offset:1024
	global_load_dword v19, v[28:29], off offset:2048
	global_load_dword v20, v[28:29], off offset:3072
	v_addc_co_u32_e32 v5, vcc, 0, v29, vcc
	v_add_co_u32_e32 v6, vcc, 0x2000, v28
	global_load_dword v21, v[4:5], off
	global_load_dword v22, v[4:5], off offset:1024
	global_load_dword v23, v[4:5], off offset:2048
	global_load_dword v24, v[4:5], off offset:3072
	v_addc_co_u32_e32 v7, vcc, 0, v29, vcc
	v_add_co_u32_e32 v28, vcc, 0x3000, v28
	global_load_dword v12, v[6:7], off
	global_load_dword v13, v[6:7], off offset:1024
	global_load_dword v4, v[6:7], off offset:2048
	global_load_dword v5, v[6:7], off offset:3072
	v_addc_co_u32_e32 v29, vcc, 0, v29, vcc
	global_load_dword v10, v[28:29], off
	global_load_dword v11, v[28:29], off offset:1024
	global_load_dword v6, v[28:29], off offset:2048
	global_load_dword v7, v[28:29], off offset:3072
	v_ashrrev_i32_e32 v15, 6, v14
	v_lshlrev_b32_e32 v26, 4, v15
	v_cmp_lt_i32_e32 vcc, v26, v2
	s_waitcnt vmcnt(16)
	ds_write_b128 v104, v[100:103] offset:18432
	s_waitcnt lgkmcnt(0)
	s_barrier
	s_and_saveexec_b64 s[4:5], vcc
	s_cbranch_execz .LBB0_1852
	v_lshl_add_u32 v25, v15, 10, v45
	ds_read_b128 v[28:31], v25 offset:18432
	ds_read_b128 v[32:35], v25 offset:18448
	ds_read_b128 v[36:39], v25 offset:18464
	ds_read_b128 v[40:43], v25 offset:18480
	s_mov_b32 s6, 0xbd800000
	s_waitcnt vmcnt(15) lgkmcnt(3)
	v_fma_f32 v25, v17, v28, v16
	s_waitcnt vmcnt(14)
	v_fmac_f32_e32 v25, v18, v29
	s_waitcnt vmcnt(13)
	v_fmac_f32_e32 v25, v19, v30
	s_waitcnt vmcnt(12)
	v_fmac_f32_e32 v25, v20, v31
	s_waitcnt vmcnt(11) lgkmcnt(2)
	v_fmac_f32_e32 v25, v21, v32
	s_waitcnt vmcnt(10)
	v_fmac_f32_e32 v25, v22, v33
	s_waitcnt vmcnt(9)
	v_fmac_f32_e32 v25, v23, v34
	s_waitcnt vmcnt(8)
	v_fmac_f32_e32 v25, v24, v35
	s_waitcnt vmcnt(6) lgkmcnt(1)
	v_pk_mul_f32 v[28:29], v[12:13], v[36:37]
	s_nop 0
	v_add_f32_e32 v25, v25, v28
	v_add_f32_e32 v25, v25, v29
	s_waitcnt vmcnt(4)
	v_pk_mul_f32 v[28:29], v[4:5], v[38:39]
	s_nop 0
	v_add_f32_e32 v25, v25, v28
	v_add_f32_e32 v25, v25, v29
	s_waitcnt vmcnt(2) lgkmcnt(0)
	v_pk_mul_f32 v[28:29], v[10:11], v[40:41]
	s_nop 0
	v_add_f32_e32 v25, v25, v28
	v_add_f32_e32 v25, v25, v29
	s_waitcnt vmcnt(0)
	v_pk_mul_f32 v[28:29], v[6:7], v[42:43]
	s_nop 0
	v_add_f32_e32 v25, v25, v28
	v_add_f32_e32 v25, v25, v29
	v_max_f32_e64 v27, -v25, 0
	v_mul_f32_e64 v25, |v25|, s90
	v_exp_f32_e32 v25, v25
	s_nop 0
	v_add_f32_e32 v25, 1.0, v25
	v_cmp_gt_f32_e32 vcc, s1, v25
	s_nop 1
	v_cndmask_b32_e64 v28, 0, 32, vcc
	v_ldexp_f32 v25, v25, v28
	v_log_f32_e32 v25, v25
	s_nop 0
	v_mul_f32_e32 v28, 0x3f317217, v25
	v_fma_f32 v28, v25, s91, -v28
	v_fmac_f32_e32 v28, 0x3377d1cf, v25
	v_fmac_f32_e32 v28, 0x3f317217, v25
	v_cmp_lt_f32_e64 s[38:39], |v25|, s84
	s_nop 1
	v_cndmask_b32_e64 v25, v25, v28, s[38:39]
	v_cndmask_b32_e32 v28, 0, v213, vcc
	v_sub_f32_e32 v25, v25, v28
	v_add_f32_e32 v25, v27, v25
	v_fma_f32 v27, v25, s6, 0

; DI void gla_bcum(const Params& p, int l, int row0, int Lc, int h, float* bc, float* tot, float* gas) {
;     ...
;   float off = 0.f;
;   for (int g = 0; g < tq; ++g) off += tot[g * 64 + kd];
; #pragma unroll
;   for (int i = 0; i < 16; ++i) bc[(tq * 16 + i) * BCS + kd] += off;
;   __syncthreads();
; DI void gla3_item(const Params& p, int l, int gi, char* smem) {
;     ...
;   {
;     const int s = tid & 63, c2 = tid >> 6;
;     const u16* GQ = (const u16*)(p.ws + O_GQ) + (size_t)(row0 + s) * 256 + h * 64;
;     const u16* GK = (const u16*)(p.ws + O_GK) + (size_t)(row0 + s) * 256 + h * 64;
;     u32x4 qv[2], kv[2], sv[4];
; #pragma unroll
;     for (int i = 0; i < 2; ++i) {
;       qv[i] = (s < Lc) ? *(const u32x4*)(GQ + (c2 + 4 * i) * 8) : u32x4{0u, 0u, 0u, 0u};
;       kv[i] = (s < Lc) ? *(const u32x4*)(GK + (c2 + 4 * i) * 8) : u32x4{0u, 0u, 0u, 0u};
;     }
; #pragma unroll
;     for (int i = 0; i < 4; ++i) { const int id = tid + i * 256; sv[i] = *(const u32x4*)(KVT + (id >> 3) * 64 + (id & 7) * 8); }
.LBB0_1886:
	s_or_b64 exec, exec, s[4:5]
	ds_read_b32 v5, v25
	v_add_u32_e32 v4, 0x110, v40
	v_and_b32_e32 v49, 63, v46
	v_readlane_b32 s4, v252, 29
	v_ashrrev_i32_e32 v48, 6, v46
	s_waitcnt lgkmcnt(0)
	v_add_f32_e32 v5, v26, v5
	ds_write_b32 v25, v5
	ds_read_b32 v5, v27
	v_readlane_b32 s5, v252, 30
	v_lshlrev_b32_e32 v8, 1, v1
	v_mov_b32_e32 v9, v173
	v_lshlrev_b32_e32 v42, 3, v48
	s_waitcnt lgkmcnt(0)
	v_add_f32_e32 v5, v26, v5
	ds_write_b32 v27, v5
	ds_read_b32 v5, v28
	v_cmp_lt_u32_e32 vcc, v49, v2
	v_ashrrev_i32_e32 v43, 31, v42
	v_add_u32_e32 v80, v49, v44
	v_ashrrev_i32_e32 v81, 31, v80
	v_lshlrev_b64 v[80:81], 9, v[80:81]
	v_lshl_add_u64 v[82:83], s[4:5], 0, v[80:81]
	v_lshl_add_u64 v[80:81], s[76:77], 0, v[80:81]
	v_lshl_add_u64 v[82:83], v[82:83], 0, v[8:9]
	v_lshl_add_u64 v[80:81], v[80:81], 0, v[8:9]
	v_lshlrev_b64 v[84:85], 1, v[42:43]
	v_lshl_add_u64 v[82:83], v[82:83], 0, v[84:85]
	v_lshl_add_u64 v[80:81], v[80:81], 0, v[84:85]
	v_mov_b32_e32 v64, 0
	v_mov_b32_e32 v65, 0
	v_mov_b32_e32 v66, 0
	v_mov_b32_e32 v67, 0
	v_mov_b32_e32 v68, 0
	v_mov_b32_e32 v69, 0
	v_mov_b32_e32 v70, 0
	v_mov_b32_e32 v71, 0
	v_mov_b32_e32 v72, 0
	v_mov_b32_e32 v73, 0
	v_mov_b32_e32 v74, 0
	v_mov_b32_e32 v75, 0
	v_mov_b32_e32 v76, 0
	v_mov_b32_e32 v77, 0
	v_mov_b32_e32 v78, 0
	v_mov_b32_e32 v79, 0
	s_and_saveexec_b64 s[34:35], vcc
	global_load_dwordx4 v[64:67], v[82:83], off
	global_load_dwordx4 v[68:71], v[80:81], off
	global_load_dwordx4 v[72:75], v[82:83], off offset:64
	global_load_dwordx4 v[76:79], v[80:81], off offset:64
	s_mov_b64 exec, s[34:35]
	s_waitcnt lgkmcnt(0)
	v_add_f32_e32 v5, v26, v5
	ds_write_b32 v28, v5
	ds_read_b32 v5, v29
	v_mov_b32_e32 v28, 0
	s_waitcnt lgkmcnt(0)
	v_add_f32_e32 v5, v26, v5
	ds_write_b32 v29, v5
	ds_read_b32 v5, v30
	v_mov_b32_e32 v29, 0
	s_waitcnt lgkmcnt(0)
	v_add_f32_e32 v5, v26, v5
	ds_write_b32 v30, v5
	ds_read_b32 v5, v31
	v_mov_b32_e32 v30, 0
	s_waitcnt lgkmcnt(0)
	v_add_f32_e32 v5, v26, v5
	ds_write_b32 v31, v5
	ds_read_b32 v5, v32
	v_mov_b32_e32 v31, 0
	s_waitcnt lgkmcnt(0)
	v_add_f32_e32 v5, v26, v5
	ds_write_b32 v32, v5
	ds_read_b32 v5, v33
	v_mov_b32_e32 v32, 0
	s_waitcnt lgkmcnt(0)
	v_add_f32_e32 v5, v26, v5
	ds_write_b32 v33, v5
	ds_read_b32 v5, v34
	v_mov_b32_e32 v33, 0
	s_waitcnt lgkmcnt(0)
	v_add_f32_e32 v5, v26, v5
	ds_write_b32 v34, v5
	ds_read_b32 v5, v35
	v_mov_b32_e32 v34, 0
	s_waitcnt lgkmcnt(0)
	v_add_f32_e32 v5, v26, v5
	ds_write_b32 v35, v5
	ds_read_b32 v5, v36
	v_mov_b32_e32 v35, 0
	s_waitcnt lgkmcnt(0)
	v_add_f32_e32 v5, v26, v5
	ds_write_b32 v36, v5
	ds_read_b32 v5, v37
	s_waitcnt lgkmcnt(0)
	v_add_f32_e32 v5, v26, v5
	ds_write_b32 v37, v5
	ds_read_b32 v5, v38
	s_waitcnt lgkmcnt(0)
	v_add_f32_e32 v5, v26, v5
	ds_write_b32 v38, v5
	ds_read_b32 v5, v39
	s_waitcnt lgkmcnt(0)
	v_add_f32_e32 v5, v26, v5
	ds_write_b32 v39, v5
	ds_read_b32 v5, v40
	s_waitcnt lgkmcnt(0)
	v_add_f32_e32 v5, v26, v5
	ds_write_b32 v40, v5
	ds_read_b32 v5, v4
	s_waitcnt lgkmcnt(0)
	v_add_f32_e32 v5, v26, v5
	ds_write_b32 v4, v5
	v_add_u32_e32 v4, v49, v44
	v_ashrrev_i32_e32 v5, 31, v4
	v_lshlrev_b64 v[4:5], 9, v[4:5]
	s_waitcnt vmcnt(0)
	v_lshl_add_u64 v[6:7], s[4:5], 0, v[4:5]
	v_lshl_add_u64 v[4:5], s[76:77], 0, v[4:5]
	v_lshl_add_u64 v[12:13], v[6:7], 0, v[8:9]
	v_lshl_add_u64 v[14:15], v[4:5], 0, v[8:9]
	v_mov_b32_e32 v8, 0
	s_waitcnt lgkmcnt(0)
	s_barrier
	v_mov_b32_e32 v32, v64
	v_mov_b32_e32 v33, v65
	v_mov_b32_e32 v34, v66
	v_mov_b32_e32 v35, v67
	v_mov_b32_e32 v28, v68
	v_mov_b32_e32 v29, v69
	v_mov_b32_e32 v30, v70
	v_mov_b32_e32 v31, v71
	v_mov_b32_e32 v8, v72
	v_mov_b32_e32 v9, v73
	v_mov_b32_e32 v10, v74
	v_mov_b32_e32 v11, v75
	v_mov_b32_e32 v4, v76
	v_mov_b32_e32 v5, v77
	v_mov_b32_e32 v6, v78
	v_mov_b32_e32 v7, v79
	v_ashrrev_i32_e32 v1, 31, v0
	v_readlane_b32 s4, v252, 63
	v_lshlrev_b64 v[12:13], 14, v[0:1]
	v_readlane_b32 s5, v253, 0
	v_lshlrev_b32_e32 v1, 3, v46
	v_lshlrev_b32_e32 v14, 4, v46
	v_lshl_add_u64 v[12:13], s[4:5], 0, v[12:13]
	v_and_b32_e32 v40, 0x70, v14
	v_mov_b32_e32 v41, v173
	v_and_b32_e32 v26, 0xffffffc0, v1
	v_lshl_add_u64 v[24:25], v[12:13], 0, v[40:41]
	v_ashrrev_i32_e32 v27, 31, v26
	v_lshl_add_u64 v[12:13], v[26:27], 1, v[24:25]
	v_add_u32_e32 v16, 0x800, v26
	v_add_u32_e32 v20, 0x1000, v26
	v_add_u32_e32 v26, 0x1800, v26
	v_mul_u32_u24_e32 v1, 0x44, v49
	v_mul_u32_u24_e32 v36, 0x48, v49
	v_ashrrev_i32_e32 v17, 31, v16
	v_ashrrev_i32_e32 v21, 31, v20
	v_ashrrev_i32_e32 v27, 31, v26
	v_lshlrev_b32_e32 v41, 1, v36
	v_lshlrev_b32_e32 v36, 2, v42
	v_lshlrev_b32_e32 v1, 2, v1
	v_lshl_add_u64 v[16:17], v[16:17], 1, v[24:25]
	v_lshl_add_u64 v[20:21], v[20:21], 1, v[24:25]
	v_lshl_add_u64 v[24:25], v[26:27], 1, v[24:25]
	v_add3_u32 v1, v45, v36, v1
	global_load_dwordx4 v[12:15], v[12:13], off
	s_waitcnt vmcnt(2)
	v_lshlrev_b32_e32 v54, 16, v32
	global_load_dwordx4 v[16:19], v[16:17], off
	v_and_b32_e32 v55, 0xffff0000, v32
	global_load_dwordx4 v[20:23], v[20:21], off
	s_waitcnt vmcnt(3)
	v_lshlrev_b32_e32 v32, 16, v28
	global_load_dwordx4 v[24:27], v[24:25], off
	ds_read_b128 v[50:53], v1
	ds_read_b128 v[36:39], v1 offset:16
	v_and_b32_e32 v28, 0xffff0000, v28
	s_waitcnt lgkmcnt(1)
	v_mul_f32_e32 v43, 0x3fb8aa3b, v50
	v_exp_f32_e32 v50, v43
	v_mul_f32_e32 v43, 0x3fb8aa3b, v51
	v_exp_f32_e32 v51, v43
	s_waitcnt lgkmcnt(0)
; DI float bf2f(u16 h) { return __uint_as_float(((unsigned)h) << 16); }
; DI unsigned pack2(float a, float b) { f32v2_t v = {a, b}; bf16v2_t r = __builtin_convertvector(v, bf16v2_t); return __builtin_bit_cast(unsigned, r); }
; DI void gla3_item(const Params& p, int l, int gi, char* smem) {
;     ...
;     for (int i = 0; i < 2; ++i) {
;       const int kd0 = (c2 + 4 * i) * 8;
;       u32x4 qo, ko;
; #pragma unroll
;       for (int e2 = 0; e2 < 4; ++e2) {
;         const float b0 = bc[s * BCS + kd0 + 2 * e2], b1 = bc[s * BCS + kd0 + 2 * e2 + 1];
;         const float e0 = __expf(b0), e1 = __expf(b1);
;         const float q0 = bf2f((u16)(qv[i][e2] & 0xffffu)) * e0, q1 = bf2f((u16)(qv[i][e2] >> 16)) * e1;
;         const float k0 = bf2f((u16)(kv[i][e2] & 0xffffu)) / e0, k1 = bf2f((u16)(kv[i][e2] >> 16)) / e1;
;         qo[e2] = pack2(q0, q1);
;         ko[e2] = pack2(k0, k1);
;       }
;       *(u32x4*)(qt + s * LP + kd0) = qo;
;       *(u32x4*)(kt_ + s * LP + kd0) = ko;
	v_mul_f32_e32 v36, 0x3fb8aa3b, v36
	v_div_scale_f32 v43, s[4:5], v50, v50, v32
	v_rcp_f32_e32 v49, v43
	v_pk_mul_f32 v[54:55], v[50:51], v[54:55]
	v_exp_f32_e32 v36, v36
	v_mul_f32_e32 v37, 0x3fb8aa3b, v37
	v_fma_f32 v56, -v43, v49, 1.0
	v_fmac_f32_e32 v49, v56, v49
	v_div_scale_f32 v56, vcc, v32, v50, v32
	v_mul_f32_e32 v57, v56, v49
	v_fma_f32 v58, -v43, v57, v56
	v_fmac_f32_e32 v57, v58, v49
	v_fma_f32 v43, -v43, v57, v56
	v_div_fmas_f32 v43, v43, v49, v57
	v_div_fixup_f32 v43, v43, v50, v32
	v_div_scale_f32 v32, s[4:5], v51, v51, v28
	v_rcp_f32_e32 v49, v32
	v_exp_f32_e32 v37, v37
	v_fma_f32 v50, -v32, v49, 1.0
	v_fmac_f32_e32 v49, v50, v49
	v_div_scale_f32 v50, vcc, v28, v51, v28
	v_mul_f32_e32 v56, v50, v49
	v_fma_f32 v57, -v32, v56, v50
	v_fmac_f32_e32 v56, v57, v49
	v_fma_f32 v32, -v32, v56, v50
	v_div_fmas_f32 v32, v32, v49, v56
	v_div_fixup_f32 v28, v32, v51, v28
	v_cvt_pk_bf16_f32 v28, v43, v28
	v_mul_f32_e32 v43, 0x3fb8aa3b, v52
	v_exp_f32_e32 v50, v43
	v_mul_f32_e32 v43, 0x3fb8aa3b, v53
	v_lshlrev_b32_e32 v52, 16, v33
	v_and_b32_e32 v53, 0xffff0000, v33
	v_lshlrev_b32_e32 v33, 16, v29
	v_exp_f32_e32 v51, v43
	v_div_scale_f32 v43, s[4:5], v50, v50, v33
	v_rcp_f32_e32 v49, v43
	v_cvt_pk_bf16_f32 v32, v54, v55
	v_and_b32_e32 v29, 0xffff0000, v29
	v_pk_mul_f32 v[52:53], v[50:51], v[52:53]
	v_fma_f32 v54, -v43, v49, 1.0
	v_fmac_f32_e32 v49, v54, v49
	v_div_scale_f32 v54, vcc, v33, v50, v33
	v_mul_f32_e32 v55, v54, v49
	v_fma_f32 v56, -v43, v55, v54
	v_fmac_f32_e32 v55, v56, v49
	v_fma_f32 v43, -v43, v55, v54
	v_div_fmas_f32 v43, v43, v49, v55
	v_div_fixup_f32 v43, v43, v50, v33
	v_div_scale_f32 v33, s[4:5], v51, v51, v29
	v_rcp_f32_e32 v49, v33
	s_nop 0
	v_fma_f32 v50, -v33, v49, 1.0
	v_fmac_f32_e32 v49, v50, v49
	v_div_scale_f32 v50, vcc, v29, v51, v29
	v_mul_f32_e32 v54, v50, v49
	v_fma_f32 v55, -v33, v54, v50
	v_fmac_f32_e32 v54, v55, v49
	v_fma_f32 v33, -v33, v54, v50
	v_div_fmas_f32 v33, v33, v49, v54
	v_div_fixup_f32 v29, v33, v51, v29
	v_lshlrev_b32_e32 v50, 16, v34
	v_and_b32_e32 v51, 0xffff0000, v34
	v_lshlrev_b32_e32 v34, 16, v30
	v_cvt_pk_bf16_f32 v29, v43, v29
	v_div_scale_f32 v43, s[4:5], v36, v36, v34
	v_rcp_f32_e32 v49, v43
	v_cvt_pk_bf16_f32 v33, v52, v53
	v_and_b32_e32 v30, 0xffff0000, v30
	v_pk_mul_f32 v[50:51], v[36:37], v[50:51]
	v_fma_f32 v52, -v43, v49, 1.0
	v_fmac_f32_e32 v49, v52, v49
	v_div_scale_f32 v52, vcc, v34, v36, v34
	v_mul_f32_e32 v53, v52, v49
	v_fma_f32 v54, -v43, v53, v52
	v_fmac_f32_e32 v53, v54, v49
	v_fma_f32 v43, -v43, v53, v52
	v_div_fmas_f32 v43, v43, v49, v53
	v_div_fixup_f32 v36, v43, v36, v34
	v_div_scale_f32 v34, s[4:5], v37, v37, v30
	v_rcp_f32_e32 v43, v34
	s_nop 0
	v_fma_f32 v49, -v34, v43, 1.0
	v_fmac_f32_e32 v43, v49, v43
	v_div_scale_f32 v49, vcc, v30, v37, v30
	v_mul_f32_e32 v52, v49, v43
	v_fma_f32 v53, -v34, v52, v49
	v_fmac_f32_e32 v52, v53, v43
	v_fma_f32 v34, -v34, v52, v49
	v_div_fmas_f32 v34, v34, v43, v52
	v_div_fixup_f32 v30, v34, v37, v30
	v_cvt_pk_bf16_f32 v30, v36, v30
	v_mul_f32_e32 v36, 0x3fb8aa3b, v38
	v_exp_f32_e32 v36, v36
	v_mul_f32_e32 v37, 0x3fb8aa3b, v39
	v_lshlrev_b32_e32 v38, 16, v35
	v_and_b32_e32 v39, 0xffff0000, v35
	v_lshlrev_b32_e32 v35, 16, v31
	v_div_scale_f32 v43, s[4:5], v36, v36, v35
	v_rcp_f32_e32 v49, v43
	v_cvt_pk_bf16_f32 v34, v50, v51
	v_exp_f32_e32 v37, v37
	v_and_b32_e32 v31, 0xffff0000, v31
	v_fma_f32 v50, -v43, v49, 1.0
	v_fmac_f32_e32 v49, v50, v49
	v_div_scale_f32 v50, vcc, v35, v36, v35
	v_mul_f32_e32 v51, v50, v49
	v_fma_f32 v52, -v43, v51, v50
	v_fmac_f32_e32 v51, v52, v49
	v_fma_f32 v43, -v43, v51, v50
	v_div_fmas_f32 v43, v43, v49, v51
	v_pk_mul_f32 v[38:39], v[36:37], v[38:39]
	v_div_fixup_f32 v36, v43, v36, v35
	v_div_scale_f32 v35, s[4:5], v37, v37, v31
	v_rcp_f32_e32 v43, v35
	s_nop 0
	v_fma_f32 v49, -v35, v43, 1.0
	v_fmac_f32_e32 v43, v49, v43
	v_div_scale_f32 v49, vcc, v31, v37, v31
	v_mul_f32_e32 v50, v49, v43
	v_fma_f32 v51, -v35, v50, v49
	v_fmac_f32_e32 v50, v51, v43
	v_fma_f32 v35, -v35, v50, v49
	v_div_fmas_f32 v35, v35, v43, v50
	v_div_fixup_f32 v31, v35, v37, v31
	v_cvt_pk_bf16_f32 v31, v36, v31
	v_lshlrev_b32_e32 v36, 1, v42
	v_cvt_pk_bf16_f32 v35, v38, v39
	v_add3_u32 v38, v45, v41, v36
	ds_write_b128 v38, v[32:35] offset:18432
	ds_write_b128 v38, v[28:31] offset:27648
	ds_read_b128 v[32:35], v1 offset:128
	ds_read_b128 v[28:31], v1 offset:144
	v_lshlrev_b32_e32 v36, 16, v8
	v_and_b32_e32 v37, 0xffff0000, v8
	s_waitcnt lgkmcnt(1)
; DI int TID() { int t = threadIdx.x & 255; asm volatile("" : "+v"(t)); return t; }
; DI float bf2f(u16 h) { return __uint_as_float(((unsigned)h) << 16); }
; DI unsigned pack2(float a, float b) { f32v2_t v = {a, b}; bf16v2_t r = __builtin_convertvector(v, bf16v2_t); return __builtin_bit_cast(unsigned, r); }
; DI void gla_load_vt(const Params& p, int row0, int Lc, int h, u16* vt) {
;   const int tid = TID(), s = tid & 63, cg4 = tid >> 6;
;   const u16* GV = (const u16*)(p.ws + O_GV) + (size_t)(row0 + s) * 512 + h * 128;
;   u32x4 v[4];
; #pragma unroll
;   for (int i = 0; i < 4; ++i) v[i] = (s < Lc) ? *(const u32x4*)(GV + (cg4 + 4 * i) * 8) : u32x4{0u, 0u, 0u, 0u};
; DI void gla3_item(const Params& p, int l, int gi, char* smem) {
;     ...
;     for (int i = 0; i < 2; ++i) {
;       const int kd0 = (c2 + 4 * i) * 8;
;       u32x4 qo, ko;
; #pragma unroll
;       for (int e2 = 0; e2 < 4; ++e2) {
;         const float b0 = bc[s * BCS + kd0 + 2 * e2], b1 = bc[s * BCS + kd0 + 2 * e2 + 1];
;         const float e0 = __expf(b0), e1 = __expf(b1);
;         const float q0 = bf2f((u16)(qv[i][e2] & 0xffffu)) * e0, q1 = bf2f((u16)(qv[i][e2] >> 16)) * e1;
;         const float k0 = bf2f((u16)(kv[i][e2] & 0xffffu)) / e0, k1 = bf2f((u16)(kv[i][e2] >> 16)) / e1;
;         qo[e2] = pack2(q0, q1);
;         ko[e2] = pack2(k0, k1);
;       }
;       *(u32x4*)(qt + s * LP + kd0) = qo;
;       *(u32x4*)(kt_ + s * LP + kd0) = ko;
;     }
; #pragma unroll
;     for (int i = 0; i < 4; ++i) { const int id = tid + i * 256; *(u32x4*)(st + (id >> 3) * LP + (id & 7) * 8) = sv[i]; }
	v_mul_f32_e32 v1, 0x3fb8aa3b, v32
	v_exp_f32_e32 v32, v1
	v_mul_f32_e32 v1, 0x3fb8aa3b, v33
	v_exp_f32_e32 v33, v1
	v_lshlrev_b32_e32 v1, 16, v4
	v_div_scale_f32 v8, s[4:5], v32, v32, v1
	v_rcp_f32_e32 v39, v8
	v_and_b32_e32 v4, 0xffff0000, v4
	v_pk_mul_f32 v[36:37], v[32:33], v[36:37]
	v_fma_f32 v41, -v8, v39, 1.0
	v_fmac_f32_e32 v39, v41, v39
	v_div_scale_f32 v41, vcc, v1, v32, v1
	v_mul_f32_e32 v42, v41, v39
	v_fma_f32 v43, -v8, v42, v41
	v_fmac_f32_e32 v42, v43, v39
	v_fma_f32 v8, -v8, v42, v41
	v_div_fmas_f32 v8, v8, v39, v42
	v_div_fixup_f32 v1, v8, v32, v1
	v_div_scale_f32 v8, s[4:5], v33, v33, v4
	v_rcp_f32_e32 v32, v8
	s_nop 0
	v_fma_f32 v39, -v8, v32, 1.0
	v_fmac_f32_e32 v32, v39, v32
	v_div_scale_f32 v39, vcc, v4, v33, v4
	v_mul_f32_e32 v41, v39, v32
	v_fma_f32 v42, -v8, v41, v39
	v_fmac_f32_e32 v41, v42, v32
	v_fma_f32 v8, -v8, v41, v39
	v_div_fmas_f32 v8, v8, v32, v41
	v_div_fixup_f32 v4, v8, v33, v4
	v_cvt_pk_bf16_f32 v4, v1, v4
	v_mul_f32_e32 v1, 0x3fb8aa3b, v34
	v_exp_f32_e32 v32, v1
	v_mul_f32_e32 v1, 0x3fb8aa3b, v35
	v_exp_f32_e32 v33, v1
	v_lshlrev_b32_e32 v1, 16, v5
	v_lshlrev_b32_e32 v34, 16, v9
	v_and_b32_e32 v35, 0xffff0000, v9
	v_div_scale_f32 v9, s[4:5], v32, v32, v1
	v_cvt_pk_bf16_f32 v8, v36, v37
	v_rcp_f32_e32 v36, v9
	v_and_b32_e32 v5, 0xffff0000, v5
	v_pk_mul_f32 v[34:35], v[32:33], v[34:35]
	v_fma_f32 v37, -v9, v36, 1.0
	v_fmac_f32_e32 v36, v37, v36
	v_div_scale_f32 v37, vcc, v1, v32, v1
	v_mul_f32_e32 v39, v37, v36
	v_fma_f32 v41, -v9, v39, v37
	v_fmac_f32_e32 v39, v41, v36
	v_fma_f32 v9, -v9, v39, v37
	v_div_fmas_f32 v9, v9, v36, v39
	v_div_fixup_f32 v1, v9, v32, v1
	v_div_scale_f32 v9, s[4:5], v33, v33, v5
	v_rcp_f32_e32 v32, v9
	s_nop 0
	v_fma_f32 v36, -v9, v32, 1.0
	v_fmac_f32_e32 v32, v36, v32
	v_div_scale_f32 v36, vcc, v5, v33, v5
	v_mul_f32_e32 v37, v36, v32
	v_fma_f32 v39, -v9, v37, v36
	v_fmac_f32_e32 v37, v39, v32
	v_fma_f32 v9, -v9, v37, v36
	v_div_fmas_f32 v9, v9, v32, v37
	v_div_fixup_f32 v5, v9, v33, v5
	v_cvt_pk_bf16_f32 v5, v1, v5
	s_waitcnt lgkmcnt(0)
	v_mul_f32_e32 v1, 0x3fb8aa3b, v28
	v_exp_f32_e32 v28, v1
	v_mul_f32_e32 v1, 0x3fb8aa3b, v29
	v_exp_f32_e32 v29, v1
	v_lshlrev_b32_e32 v1, 16, v6
	v_lshlrev_b32_e32 v32, 16, v10
	v_and_b32_e32 v33, 0xffff0000, v10
	v_div_scale_f32 v10, s[4:5], v28, v28, v1
	v_cvt_pk_bf16_f32 v9, v34, v35
	v_rcp_f32_e32 v34, v10
	v_and_b32_e32 v6, 0xffff0000, v6
	v_pk_mul_f32 v[32:33], v[28:29], v[32:33]
	v_fma_f32 v35, -v10, v34, 1.0
	v_fmac_f32_e32 v34, v35, v34
	v_div_scale_f32 v35, vcc, v1, v28, v1
	v_mul_f32_e32 v36, v35, v34
	v_fma_f32 v37, -v10, v36, v35
	v_fmac_f32_e32 v36, v37, v34
	v_fma_f32 v10, -v10, v36, v35
	v_div_fmas_f32 v10, v10, v34, v36
	v_div_fixup_f32 v1, v10, v28, v1
	v_div_scale_f32 v10, s[4:5], v29, v29, v6
	v_rcp_f32_e32 v28, v10
	s_nop 0
	v_fma_f32 v34, -v10, v28, 1.0
	v_fmac_f32_e32 v28, v34, v28
	v_div_scale_f32 v34, vcc, v6, v29, v6
	v_mul_f32_e32 v35, v34, v28
	v_fma_f32 v36, -v10, v35, v34
	v_fmac_f32_e32 v35, v36, v28
	v_fma_f32 v10, -v10, v35, v34
	v_div_fmas_f32 v10, v10, v28, v35
	v_div_fixup_f32 v6, v10, v29, v6
	v_cvt_pk_bf16_f32 v6, v1, v6
	v_mul_f32_e32 v1, 0x3fb8aa3b, v30
	v_exp_f32_e32 v28, v1
	v_mul_f32_e32 v1, 0x3fb8aa3b, v31
	v_exp_f32_e32 v29, v1
	v_lshlrev_b32_e32 v1, 16, v7
	v_lshlrev_b32_e32 v30, 16, v11
	v_and_b32_e32 v31, 0xffff0000, v11
	v_div_scale_f32 v11, s[4:5], v28, v28, v1
	v_cvt_pk_bf16_f32 v10, v32, v33
	v_rcp_f32_e32 v32, v11
	v_and_b32_e32 v7, 0xffff0000, v7
	v_pk_mul_f32 v[30:31], v[28:29], v[30:31]
	v_fma_f32 v33, -v11, v32, 1.0
	v_fmac_f32_e32 v32, v33, v32
	v_div_scale_f32 v33, vcc, v1, v28, v1
	v_mul_f32_e32 v34, v33, v32
	v_fma_f32 v35, -v11, v34, v33
	v_fmac_f32_e32 v34, v35, v32
	v_fma_f32 v11, -v11, v34, v33
	v_div_fmas_f32 v11, v11, v32, v34
	v_div_fixup_f32 v1, v11, v28, v1
	v_div_scale_f32 v11, s[4:5], v29, v29, v7
	v_rcp_f32_e32 v28, v11
	s_nop 0
	v_fma_f32 v32, -v11, v28, 1.0
	v_fmac_f32_e32 v28, v32, v28
	v_div_scale_f32 v32, vcc, v7, v29, v7
	v_mul_f32_e32 v33, v32, v28
	v_fma_f32 v34, -v11, v33, v32
	v_fmac_f32_e32 v33, v34, v28
	v_fma_f32 v11, -v11, v33, v32
	v_div_fmas_f32 v11, v11, v28, v33
	v_div_fixup_f32 v7, v11, v29, v7
	v_cvt_pk_bf16_f32 v11, v30, v31
	v_cvt_pk_bf16_f32 v7, v1, v7
	ds_write_b128 v38, v[8:11] offset:18496
	ds_write_b128 v38, v[4:7] offset:27712
	v_add_u32_e32 v4, v45, v40
	v_lshrrev_b32_e32 v1, 3, v46
	v_mad_u64_u32 v[6:7], s[4:5], v1, s70, v[4:5]
	v_add_u32_e32 v1, 0x100, v46
	v_lshrrev_b32_e32 v1, 3, v1
	s_waitcnt vmcnt(3)
	ds_write_b128 v6, v[12:15] offset:55296
	v_mad_u64_u32 v[6:7], s[4:5], v1, s70, v[4:5]
	v_add_u32_e32 v1, 0x200, v46
	v_lshrrev_b32_e32 v1, 3, v1
	s_waitcnt vmcnt(2)
	ds_write_b128 v6, v[16:19] offset:55296
	v_mad_u64_u32 v[6:7], s[4:5], v1, s70, v[4:5]
	v_add_u32_e32 v1, 0x300, v46
	v_lshrrev_b32_e32 v1, 3, v1
	v_mad_u64_u32 v[4:5], s[4:5], v1, s70, v[4:5]
	v_mov_b32_e32 v1, v185
	s_waitcnt vmcnt(1)
	ds_write_b128 v6, v[20:23] offset:55296
	s_waitcnt vmcnt(0)
	ds_write_b128 v4, v[24:27] offset:55296
	v_readlane_b32 s4, v252, 37
	v_and_b32_e32 v24, 63, v1
	v_add_u32_e32 v4, v24, v44
	v_ashrrev_i32_e32 v5, 31, v4
	v_lshlrev_b64 v[4:5], 10, v[4:5]
	v_readlane_b32 s5, v252, 38
	v_ashrrev_i32_e32 v1, 3, v1
	v_and_b32_e32 v20, -8, v1
	v_lshl_add_u64 v[4:5], s[4:5], 0, v[4:5]
	v_lshl_add_u64 v[22:23], v[4:5], 0, v[172:173]
	v_cmp_lt_u32_e32 vcc, v24, v2
	v_mov_b32_e32 v4, 0
	v_ashrrev_i32_e32 v21, 31, v20
	v_mov_b32_e32 v8, 0
	v_mov_b32_e32 v9, 0
	v_mov_b32_e32 v10, 0
	v_mov_b32_e32 v11, 0
	s_and_saveexec_b64 s[4:5], vcc
	s_cbranch_execz .LBB0_1892
	v_lshl_add_u64 v[6:7], v[20:21], 1, v[22:23]
	global_load_dwordx4 v[8:11], v[6:7], off

; DI float bf2f(u16 h) { return __uint_as_float(((unsigned)h) << 16); }
; DI float sigmoidf_(float x) { return __builtin_amdgcn_rcpf(1.f + __expf(-x)); }
; DI void img_barrier() { asm volatile("s_waitcnt lgkmcnt(0)" ::: "memory"); __builtin_amdgcn_s_barrier(); }
; DI void gate_tile(const Params& p, int l, int mt, int nt, char* smem) {
;     ...
;   EPI_IDS;
;   u16* Y = (u16*)(p.ws + O_YP) + (size_t)row0 * 3072 + col0;
;   const float* bm = p.in[26] + (size_t)l * 3072 + col0 + wc * 64 + fr;
;   img_load_bf16(Y, 3072, smem, 256, 0);
;   img_barrier();
;   u16* img = (u16*)smem + (wr * 128 + fq * 4) * IMG_LD + wc * 64 + fr;
; #pragma unroll
;   for (int n = 0; n < 4; ++n) {
;     const float bv = bm[n * 16];
; #pragma unroll
;     for (int m = 0; m < 8; ++m)
; #pragma unroll
;       for (int j = 0; j < 4; ++j) {
;         u16* q = img + (m * 16 + j) * IMG_LD + n * 16;
;         *q = f2bf(sigmoidf_(acc[m][n][j] + bv) * bf2f(*q));
;       }
;   }
.LBB0_2020:
	s_or_b64 exec, exec, s[6:7]
	s_lshl_b64 s[4:5], s[4:5], 2
	s_add_u32 s4, s12, s4
	v_and_b32_e32 v2, 0xc0, v132
	s_addc_u32 s5, s13, s5
	v_lshlrev_b32_e32 v172, 2, v2
	v_and_b32_e32 v133, 15, v132
	v_lshrrev_b32_e32 v134, 1, v132
	v_lshrrev_b32_e32 v132, 2, v132
	v_lshl_add_u64 v[0:1], s[4:5], 0, v[172:173]
	v_and_b32_e32 v132, 12, v132
	s_mov_b32 s4, 0xfffff80
	v_and_or_b32 v132, v134, s4, v132
	v_lshlrev_b32_e32 v172, 2, v133
	v_mul_lo_u32 v132, v132, s3
	v_lshl_add_u64 v[0:1], v[0:1], 0, v[172:173]
	v_add_u32_e32 v132, 16, v132
	v_lshlrev_b32_e32 v2, 1, v2
	v_lshlrev_b32_e32 v133, 1, v133
	s_waitcnt lgkmcnt(0)
	s_barrier
	v_add3_u32 v2, v132, v2, v133
	s_mov_b32 s28, 0x8000
	s_add_i32 s20, s20, 1
	s_mov_b64 s[6:7], 0
	ds_read_u16 v134, v2
	ds_read_u16 v135, v2 offset:528
	ds_read_u16 v136, v2 offset:1056
	ds_read_u16 v137, v2 offset:1584
	ds_read_u16 v138, v2 offset:8448
	ds_read_u16 v139, v2 offset:8976
	ds_read_u16 v140, v2 offset:9504
	ds_read_u16 v141, v2 offset:10032
	s_waitcnt lgkmcnt(4)
	v_lshlrev_b32_e32 v134, 16, v134
	v_lshlrev_b32_e32 v135, 16, v135
	v_lshlrev_b32_e32 v136, 16, v136
	v_lshlrev_b32_e32 v137, 16, v137
	v_pk_mul_f32 v[128:129], v[128:129], v[134:135]
	v_pk_mul_f32 v[130:131], v[130:131], v[136:137]
	v_cvt_pk_bf16_f32 v146, v128, v129
	v_cvt_pk_bf16_f32 v147, v130, v131
	ds_write_b16 v2, v146
	ds_write_b16_d16_hi v2, v146 offset:528
	ds_write_b16 v2, v147 offset:1056
	ds_write_b16_d16_hi v2, v147 offset:1584
	ds_read_u16 v134, v2 offset:16896
	ds_read_u16 v135, v2 offset:17424
	ds_read_u16 v136, v2 offset:17952
	ds_read_u16 v137, v2 offset:18480
	s_waitcnt lgkmcnt(8)
	v_lshlrev_b32_e32 v138, 16, v138
	v_lshlrev_b32_e32 v139, 16, v139
	v_lshlrev_b32_e32 v140, 16, v140
	v_lshlrev_b32_e32 v141, 16, v141
	v_pk_mul_f32 v[124:125], v[124:125], v[138:139]
	v_pk_mul_f32 v[126:127], v[126:127], v[140:141]
	v_cvt_pk_bf16_f32 v146, v124, v125
	v_cvt_pk_bf16_f32 v147, v126, v127
	ds_write_b16 v2, v146 offset:8448
	ds_write_b16_d16_hi v2, v146 offset:8976
	ds_write_b16 v2, v147 offset:9504
	ds_write_b16_d16_hi v2, v147 offset:10032
	ds_read_u16 v138, v2 offset:25344
	ds_read_u16 v139, v2 offset:25872
	ds_read_u16 v140, v2 offset:26400
	ds_read_u16 v141, v2 offset:26928
	s_waitcnt lgkmcnt(8)
	v_lshlrev_b32_e32 v134, 16, v134
	v_lshlrev_b32_e32 v135, 16, v135
	v_lshlrev_b32_e32 v136, 16, v136
	v_lshlrev_b32_e32 v137, 16, v137
	v_pk_mul_f32 v[120:121], v[120:121], v[134:135]
	v_pk_mul_f32 v[122:123], v[122:123], v[136:137]
	v_cvt_pk_bf16_f32 v146, v120, v121
	v_cvt_pk_bf16_f32 v147, v122, v123
	ds_write_b16 v2, v146 offset:16896
	ds_write_b16_d16_hi v2, v146 offset:17424
	ds_write_b16 v2, v147 offset:17952
	ds_write_b16_d16_hi v2, v147 offset:18480
	ds_read_u16 v134, v2 offset:33792
	ds_read_u16 v135, v2 offset:34320
	ds_read_u16 v136, v2 offset:34848
	ds_read_u16 v137, v2 offset:35376
	s_waitcnt lgkmcnt(8)
	v_lshlrev_b32_e32 v138, 16, v138
	v_lshlrev_b32_e32 v139, 16, v139
	v_lshlrev_b32_e32 v140, 16, v140
	v_lshlrev_b32_e32 v141, 16, v141
	v_pk_mul_f32 v[116:117], v[116:117], v[138:139]
	v_pk_mul_f32 v[118:119], v[118:119], v[140:141]
	v_cvt_pk_bf16_f32 v146, v116, v117
	v_cvt_pk_bf16_f32 v147, v118, v119
	ds_write_b16 v2, v146 offset:25344
	ds_write_b16_d16_hi v2, v146 offset:25872
	ds_write_b16 v2, v147 offset:26400
	ds_write_b16_d16_hi v2, v147 offset:26928
	ds_read_u16 v138, v2 offset:42240
	ds_read_u16 v139, v2 offset:42768
	ds_read_u16 v140, v2 offset:43296
	ds_read_u16 v141, v2 offset:43824
	s_waitcnt lgkmcnt(8)
	v_lshlrev_b32_e32 v134, 16, v134
	v_lshlrev_b32_e32 v135, 16, v135
	v_lshlrev_b32_e32 v136, 16, v136
	v_lshlrev_b32_e32 v137, 16, v137
	v_pk_mul_f32 v[112:113], v[112:113], v[134:135]
	v_pk_mul_f32 v[114:115], v[114:115], v[136:137]
	v_cvt_pk_bf16_f32 v146, v112, v113
	v_cvt_pk_bf16_f32 v147, v114, v115
	ds_write_b16 v2, v146 offset:33792
	ds_write_b16_d16_hi v2, v146 offset:34320
	ds_write_b16 v2, v147 offset:34848
	ds_write_b16_d16_hi v2, v147 offset:35376
	ds_read_u16 v134, v2 offset:50688
	ds_read_u16 v135, v2 offset:51216
	ds_read_u16 v136, v2 offset:51744
	ds_read_u16 v137, v2 offset:52272
	s_waitcnt lgkmcnt(8)
	v_lshlrev_b32_e32 v138, 16, v138
	v_lshlrev_b32_e32 v139, 16, v139
	v_lshlrev_b32_e32 v140, 16, v140
	v_lshlrev_b32_e32 v141, 16, v141
	v_pk_mul_f32 v[108:109], v[108:109], v[138:139]
	v_pk_mul_f32 v[110:111], v[110:111], v[140:141]
	v_cvt_pk_bf16_f32 v146, v108, v109
	v_cvt_pk_bf16_f32 v147, v110, v111
	ds_write_b16 v2, v146 offset:42240
	ds_write_b16_d16_hi v2, v146 offset:42768
	ds_write_b16 v2, v147 offset:43296
	ds_write_b16_d16_hi v2, v147 offset:43824
	ds_read_u16 v138, v2 offset:59136
	ds_read_u16 v139, v2 offset:59664
	ds_read_u16 v140, v2 offset:60192
	ds_read_u16 v141, v2 offset:60720
	s_waitcnt lgkmcnt(8)
	v_lshlrev_b32_e32 v134, 16, v134
	v_lshlrev_b32_e32 v135, 16, v135
	v_lshlrev_b32_e32 v136, 16, v136
	v_lshlrev_b32_e32 v137, 16, v137
	v_pk_mul_f32 v[104:105], v[104:105], v[134:135]
	v_pk_mul_f32 v[106:107], v[106:107], v[136:137]
	v_cvt_pk_bf16_f32 v146, v104, v105
	v_cvt_pk_bf16_f32 v147, v106, v107
	ds_write_b16 v2, v146 offset:50688
	ds_write_b16_d16_hi v2, v146 offset:51216
	ds_write_b16 v2, v147 offset:51744
	ds_write_b16_d16_hi v2, v147 offset:52272
	ds_read_u16 v134, v2 offset:32
	ds_read_u16 v135, v2 offset:560
	ds_read_u16 v136, v2 offset:1088
	ds_read_u16 v137, v2 offset:1616
	s_waitcnt lgkmcnt(8)
; DI float bf2f(u16 h) { return __uint_as_float(((unsigned)h) << 16); }
; DI float sigmoidf_(float x) { return __builtin_amdgcn_rcpf(1.f + __expf(-x)); }
; DI void gate_tile(const Params& p, int l, int mt, int nt, char* smem) {
;     ...
;   u16* img = (u16*)smem + (wr * 128 + fq * 4) * IMG_LD + wc * 64 + fr;
; #pragma unroll
;   for (int n = 0; n < 4; ++n) {
;     const float bv = bm[n * 16];
; #pragma unroll
;     for (int m = 0; m < 8; ++m)
; #pragma unroll
;       for (int j = 0; j < 4; ++j) {
;         u16* q = img + (m * 16 + j) * IMG_LD + n * 16;
;         *q = f2bf(sigmoidf_(acc[m][n][j] + bv) * bf2f(*q));
;       }
;   }
	v_lshlrev_b32_e32 v138, 16, v138
	v_lshlrev_b32_e32 v139, 16, v139
	v_lshlrev_b32_e32 v140, 16, v140
	v_lshlrev_b32_e32 v141, 16, v141
	v_pk_mul_f32 v[100:101], v[100:101], v[138:139]
	v_pk_mul_f32 v[102:103], v[102:103], v[140:141]
	v_cvt_pk_bf16_f32 v146, v100, v101
	v_cvt_pk_bf16_f32 v147, v102, v103
	ds_write_b16 v2, v146 offset:59136
	ds_write_b16_d16_hi v2, v146 offset:59664
	ds_write_b16 v2, v147 offset:60192
	ds_write_b16_d16_hi v2, v147 offset:60720
	ds_read_u16 v138, v2 offset:8480
	ds_read_u16 v139, v2 offset:9008
	ds_read_u16 v140, v2 offset:9536
	ds_read_u16 v141, v2 offset:10064
	s_waitcnt lgkmcnt(8)
	v_lshlrev_b32_e32 v134, 16, v134
	v_lshlrev_b32_e32 v135, 16, v135
	v_lshlrev_b32_e32 v136, 16, v136
	v_lshlrev_b32_e32 v137, 16, v137
	v_pk_mul_f32 v[96:97], v[96:97], v[134:135]
	v_pk_mul_f32 v[98:99], v[98:99], v[136:137]
	v_cvt_pk_bf16_f32 v146, v96, v97
	v_cvt_pk_bf16_f32 v147, v98, v99
	ds_write_b16 v2, v146 offset:32
	ds_write_b16_d16_hi v2, v146 offset:560
	ds_write_b16 v2, v147 offset:1088
	ds_write_b16_d16_hi v2, v147 offset:1616
	ds_read_u16 v134, v2 offset:16928
	ds_read_u16 v135, v2 offset:17456
	ds_read_u16 v136, v2 offset:17984
	ds_read_u16 v137, v2 offset:18512
	s_waitcnt lgkmcnt(8)
	v_lshlrev_b32_e32 v138, 16, v138
	v_lshlrev_b32_e32 v139, 16, v139
	v_lshlrev_b32_e32 v140, 16, v140
	v_lshlrev_b32_e32 v141, 16, v141
	v_pk_mul_f32 v[92:93], v[92:93], v[138:139]
	v_pk_mul_f32 v[94:95], v[94:95], v[140:141]
	v_cvt_pk_bf16_f32 v146, v92, v93
	v_cvt_pk_bf16_f32 v147, v94, v95
	ds_write_b16 v2, v146 offset:8480
	ds_write_b16_d16_hi v2, v146 offset:9008
	ds_write_b16 v2, v147 offset:9536
	ds_write_b16_d16_hi v2, v147 offset:10064
	ds_read_u16 v138, v2 offset:25376
	ds_read_u16 v139, v2 offset:25904
	ds_read_u16 v140, v2 offset:26432
	ds_read_u16 v141, v2 offset:26960
	s_waitcnt lgkmcnt(8)
	v_lshlrev_b32_e32 v134, 16, v134
	v_lshlrev_b32_e32 v135, 16, v135
	v_lshlrev_b32_e32 v136, 16, v136
	v_lshlrev_b32_e32 v137, 16, v137
	v_pk_mul_f32 v[88:89], v[88:89], v[134:135]
	v_pk_mul_f32 v[90:91], v[90:91], v[136:137]
	v_cvt_pk_bf16_f32 v146, v88, v89
	v_cvt_pk_bf16_f32 v147, v90, v91
	ds_write_b16 v2, v146 offset:16928
	ds_write_b16_d16_hi v2, v146 offset:17456
	ds_write_b16 v2, v147 offset:17984
	ds_write_b16_d16_hi v2, v147 offset:18512
	ds_read_u16 v134, v2 offset:33824
	ds_read_u16 v135, v2 offset:34352
	ds_read_u16 v136, v2 offset:34880
	ds_read_u16 v137, v2 offset:35408
	s_waitcnt lgkmcnt(8)
	v_lshlrev_b32_e32 v138, 16, v138
	v_lshlrev_b32_e32 v139, 16, v139
	v_lshlrev_b32_e32 v140, 16, v140
	v_lshlrev_b32_e32 v141, 16, v141
	v_pk_mul_f32 v[84:85], v[84:85], v[138:139]
	v_pk_mul_f32 v[86:87], v[86:87], v[140:141]
	v_cvt_pk_bf16_f32 v146, v84, v85
	v_cvt_pk_bf16_f32 v147, v86, v87
	ds_write_b16 v2, v146 offset:25376
	ds_write_b16_d16_hi v2, v146 offset:25904
	ds_write_b16 v2, v147 offset:26432
	ds_write_b16_d16_hi v2, v147 offset:26960
	ds_read_u16 v138, v2 offset:42272
	ds_read_u16 v139, v2 offset:42800
	ds_read_u16 v140, v2 offset:43328
	ds_read_u16 v141, v2 offset:43856
	s_waitcnt lgkmcnt(8)
	v_lshlrev_b32_e32 v134, 16, v134
	v_lshlrev_b32_e32 v135, 16, v135
	v_lshlrev_b32_e32 v136, 16, v136
	v_lshlrev_b32_e32 v137, 16, v137
	v_pk_mul_f32 v[80:81], v[80:81], v[134:135]
	v_pk_mul_f32 v[82:83], v[82:83], v[136:137]
	v_cvt_pk_bf16_f32 v146, v80, v81
	v_cvt_pk_bf16_f32 v147, v82, v83
	ds_write_b16 v2, v146 offset:33824
	ds_write_b16_d16_hi v2, v146 offset:34352
	ds_write_b16 v2, v147 offset:34880
	ds_write_b16_d16_hi v2, v147 offset:35408
	ds_read_u16 v134, v2 offset:50720
	ds_read_u16 v135, v2 offset:51248
	ds_read_u16 v136, v2 offset:51776
	ds_read_u16 v137, v2 offset:52304
	s_waitcnt lgkmcnt(8)
	v_lshlrev_b32_e32 v138, 16, v138
	v_lshlrev_b32_e32 v139, 16, v139
	v_lshlrev_b32_e32 v140, 16, v140
	v_lshlrev_b32_e32 v141, 16, v141
	v_pk_mul_f32 v[76:77], v[76:77], v[138:139]
	v_pk_mul_f32 v[78:79], v[78:79], v[140:141]
	v_cvt_pk_bf16_f32 v146, v76, v77
	v_cvt_pk_bf16_f32 v147, v78, v79
	ds_write_b16 v2, v146 offset:42272
	ds_write_b16_d16_hi v2, v146 offset:42800
	ds_write_b16 v2, v147 offset:43328
	ds_write_b16_d16_hi v2, v147 offset:43856
	ds_read_u16 v138, v2 offset:59168
	ds_read_u16 v139, v2 offset:59696
	ds_read_u16 v140, v2 offset:60224
	ds_read_u16 v141, v2 offset:60752
	s_waitcnt lgkmcnt(8)
	v_lshlrev_b32_e32 v134, 16, v134
	v_lshlrev_b32_e32 v135, 16, v135
	v_lshlrev_b32_e32 v136, 16, v136
	v_lshlrev_b32_e32 v137, 16, v137
	v_pk_mul_f32 v[72:73], v[72:73], v[134:135]
	v_pk_mul_f32 v[74:75], v[74:75], v[136:137]
	v_cvt_pk_bf16_f32 v146, v72, v73
	v_cvt_pk_bf16_f32 v147, v74, v75
	ds_write_b16 v2, v146 offset:50720
	ds_write_b16_d16_hi v2, v146 offset:51248
	ds_write_b16 v2, v147 offset:51776
	ds_write_b16_d16_hi v2, v147 offset:52304
	ds_read_u16 v134, v2 offset:64
	ds_read_u16 v135, v2 offset:592
	ds_read_u16 v136, v2 offset:1120
	ds_read_u16 v137, v2 offset:1648
	s_waitcnt lgkmcnt(8)
	v_lshlrev_b32_e32 v138, 16, v138
	v_lshlrev_b32_e32 v139, 16, v139
	v_lshlrev_b32_e32 v140, 16, v140
	v_lshlrev_b32_e32 v141, 16, v141
	v_pk_mul_f32 v[68:69], v[68:69], v[138:139]
	v_pk_mul_f32 v[70:71], v[70:71], v[140:141]
	v_cvt_pk_bf16_f32 v146, v68, v69
	v_cvt_pk_bf16_f32 v147, v70, v71
	ds_write_b16 v2, v146 offset:59168
	ds_write_b16_d16_hi v2, v146 offset:59696
	ds_write_b16 v2, v147 offset:60224
	ds_write_b16_d16_hi v2, v147 offset:60752
	ds_read_u16 v138, v2 offset:8512
	ds_read_u16 v139, v2 offset:9040
	ds_read_u16 v140, v2 offset:9568
	ds_read_u16 v141, v2 offset:10096
	s_waitcnt lgkmcnt(8)
; DI float bf2f(u16 h) { return __uint_as_float(((unsigned)h) << 16); }
; DI float sigmoidf_(float x) { return __builtin_amdgcn_rcpf(1.f + __expf(-x)); }
; DI void gate_tile(const Params& p, int l, int mt, int nt, char* smem) {
;     ...
;   u16* img = (u16*)smem + (wr * 128 + fq * 4) * IMG_LD + wc * 64 + fr;
; #pragma unroll
;   for (int n = 0; n < 4; ++n) {
;     const float bv = bm[n * 16];
; #pragma unroll
;     for (int m = 0; m < 8; ++m)
; #pragma unroll
;       for (int j = 0; j < 4; ++j) {
;         u16* q = img + (m * 16 + j) * IMG_LD + n * 16;
;         *q = f2bf(sigmoidf_(acc[m][n][j] + bv) * bf2f(*q));
;       }
;   }
	v_lshlrev_b32_e32 v134, 16, v134
	v_lshlrev_b32_e32 v135, 16, v135
	v_lshlrev_b32_e32 v136, 16, v136
	v_lshlrev_b32_e32 v137, 16, v137
	v_pk_mul_f32 v[64:65], v[64:65], v[134:135]
	v_pk_mul_f32 v[66:67], v[66:67], v[136:137]
	v_cvt_pk_bf16_f32 v146, v64, v65
	v_cvt_pk_bf16_f32 v147, v66, v67
	ds_write_b16 v2, v146 offset:64
	ds_write_b16_d16_hi v2, v146 offset:592
	ds_write_b16 v2, v147 offset:1120
	ds_write_b16_d16_hi v2, v147 offset:1648
	ds_read_u16 v134, v2 offset:16960
	ds_read_u16 v135, v2 offset:17488
	ds_read_u16 v136, v2 offset:18016
	ds_read_u16 v137, v2 offset:18544
	s_waitcnt lgkmcnt(8)
	v_lshlrev_b32_e32 v138, 16, v138
	v_lshlrev_b32_e32 v139, 16, v139
	v_lshlrev_b32_e32 v140, 16, v140
	v_lshlrev_b32_e32 v141, 16, v141
	v_pk_mul_f32 v[60:61], v[60:61], v[138:139]
	v_pk_mul_f32 v[62:63], v[62:63], v[140:141]
	v_cvt_pk_bf16_f32 v146, v60, v61
	v_cvt_pk_bf16_f32 v147, v62, v63
	ds_write_b16 v2, v146 offset:8512
	ds_write_b16_d16_hi v2, v146 offset:9040
	ds_write_b16 v2, v147 offset:9568
	ds_write_b16_d16_hi v2, v147 offset:10096
	ds_read_u16 v138, v2 offset:25408
	ds_read_u16 v139, v2 offset:25936
	ds_read_u16 v140, v2 offset:26464
	ds_read_u16 v141, v2 offset:26992
	s_waitcnt lgkmcnt(8)
	v_lshlrev_b32_e32 v134, 16, v134
	v_lshlrev_b32_e32 v135, 16, v135
	v_lshlrev_b32_e32 v136, 16, v136
	v_lshlrev_b32_e32 v137, 16, v137
	v_pk_mul_f32 v[56:57], v[56:57], v[134:135]
	v_pk_mul_f32 v[58:59], v[58:59], v[136:137]
	v_cvt_pk_bf16_f32 v146, v56, v57
	v_cvt_pk_bf16_f32 v147, v58, v59
	ds_write_b16 v2, v146 offset:16960
	ds_write_b16_d16_hi v2, v146 offset:17488
	ds_write_b16 v2, v147 offset:18016
	ds_write_b16_d16_hi v2, v147 offset:18544
	ds_read_u16 v134, v2 offset:33856
	ds_read_u16 v135, v2 offset:34384
	ds_read_u16 v136, v2 offset:34912
	ds_read_u16 v137, v2 offset:35440
	s_waitcnt lgkmcnt(8)
	v_lshlrev_b32_e32 v138, 16, v138
	v_lshlrev_b32_e32 v139, 16, v139
	v_lshlrev_b32_e32 v140, 16, v140
	v_lshlrev_b32_e32 v141, 16, v141
	v_pk_mul_f32 v[52:53], v[52:53], v[138:139]
	v_pk_mul_f32 v[54:55], v[54:55], v[140:141]
	v_cvt_pk_bf16_f32 v146, v52, v53
	v_cvt_pk_bf16_f32 v147, v54, v55
	ds_write_b16 v2, v146 offset:25408
	ds_write_b16_d16_hi v2, v146 offset:25936
	ds_write_b16 v2, v147 offset:26464
	ds_write_b16_d16_hi v2, v147 offset:26992
	ds_read_u16 v138, v2 offset:42304
	ds_read_u16 v139, v2 offset:42832
	ds_read_u16 v140, v2 offset:43360
	ds_read_u16 v141, v2 offset:43888
	s_waitcnt lgkmcnt(8)
	v_lshlrev_b32_e32 v134, 16, v134
	v_lshlrev_b32_e32 v135, 16, v135
	v_lshlrev_b32_e32 v136, 16, v136
	v_lshlrev_b32_e32 v137, 16, v137
	v_pk_mul_f32 v[48:49], v[48:49], v[134:135]
	v_pk_mul_f32 v[50:51], v[50:51], v[136:137]
	v_cvt_pk_bf16_f32 v146, v48, v49
	v_cvt_pk_bf16_f32 v147, v50, v51
	ds_write_b16 v2, v146 offset:33856
	ds_write_b16_d16_hi v2, v146 offset:34384
	ds_write_b16 v2, v147 offset:34912
	ds_write_b16_d16_hi v2, v147 offset:35440
	ds_read_u16 v134, v2 offset:50752
	ds_read_u16 v135, v2 offset:51280
	ds_read_u16 v136, v2 offset:51808
	ds_read_u16 v137, v2 offset:52336
	s_waitcnt lgkmcnt(8)
	v_lshlrev_b32_e32 v138, 16, v138
	v_lshlrev_b32_e32 v139, 16, v139
	v_lshlrev_b32_e32 v140, 16, v140
	v_lshlrev_b32_e32 v141, 16, v141
	v_pk_mul_f32 v[44:45], v[44:45], v[138:139]
	v_pk_mul_f32 v[46:47], v[46:47], v[140:141]
	v_cvt_pk_bf16_f32 v146, v44, v45
	v_cvt_pk_bf16_f32 v147, v46, v47
	ds_write_b16 v2, v146 offset:42304
	ds_write_b16_d16_hi v2, v146 offset:42832
	ds_write_b16 v2, v147 offset:43360
	ds_write_b16_d16_hi v2, v147 offset:43888
	ds_read_u16 v138, v2 offset:59200
	ds_read_u16 v139, v2 offset:59728
	ds_read_u16 v140, v2 offset:60256
	ds_read_u16 v141, v2 offset:60784
	s_waitcnt lgkmcnt(8)
	v_lshlrev_b32_e32 v134, 16, v134
	v_lshlrev_b32_e32 v135, 16, v135
	v_lshlrev_b32_e32 v136, 16, v136
	v_lshlrev_b32_e32 v137, 16, v137
	v_pk_mul_f32 v[40:41], v[40:41], v[134:135]
	v_pk_mul_f32 v[42:43], v[42:43], v[136:137]
	v_cvt_pk_bf16_f32 v146, v40, v41
	v_cvt_pk_bf16_f32 v147, v42, v43
	ds_write_b16 v2, v146 offset:50752
	ds_write_b16_d16_hi v2, v146 offset:51280
	ds_write_b16 v2, v147 offset:51808
	ds_write_b16_d16_hi v2, v147 offset:52336
	ds_read_u16 v134, v2 offset:96
	ds_read_u16 v135, v2 offset:624
	ds_read_u16 v136, v2 offset:1152
	ds_read_u16 v137, v2 offset:1680
	s_waitcnt lgkmcnt(8)
	v_lshlrev_b32_e32 v138, 16, v138
	v_lshlrev_b32_e32 v139, 16, v139
	v_lshlrev_b32_e32 v140, 16, v140
	v_lshlrev_b32_e32 v141, 16, v141
	v_pk_mul_f32 v[36:37], v[36:37], v[138:139]
	v_pk_mul_f32 v[38:39], v[38:39], v[140:141]
	v_cvt_pk_bf16_f32 v146, v36, v37
	v_cvt_pk_bf16_f32 v147, v38, v39
	ds_write_b16 v2, v146 offset:59200
	ds_write_b16_d16_hi v2, v146 offset:59728
	ds_write_b16 v2, v147 offset:60256
	ds_write_b16_d16_hi v2, v147 offset:60784
	ds_read_u16 v138, v2 offset:8544
	ds_read_u16 v139, v2 offset:9072
	ds_read_u16 v140, v2 offset:9600
	ds_read_u16 v141, v2 offset:10128
	s_waitcnt lgkmcnt(8)
	v_lshlrev_b32_e32 v134, 16, v134
	v_lshlrev_b32_e32 v135, 16, v135
	v_lshlrev_b32_e32 v136, 16, v136
	v_lshlrev_b32_e32 v137, 16, v137
	v_pk_mul_f32 v[32:33], v[32:33], v[134:135]
	v_pk_mul_f32 v[34:35], v[34:35], v[136:137]
	v_cvt_pk_bf16_f32 v146, v32, v33
	v_cvt_pk_bf16_f32 v147, v34, v35
	ds_write_b16 v2, v146 offset:96
	ds_write_b16_d16_hi v2, v146 offset:624
	ds_write_b16 v2, v147 offset:1152
	ds_write_b16_d16_hi v2, v147 offset:1680
	ds_read_u16 v134, v2 offset:16992
	ds_read_u16 v135, v2 offset:17520
	ds_read_u16 v136, v2 offset:18048
	ds_read_u16 v137, v2 offset:18576
	s_waitcnt lgkmcnt(8)
; DI float bf2f(u16 h) { return __uint_as_float(((unsigned)h) << 16); }
; DI float sigmoidf_(float x) { return __builtin_amdgcn_rcpf(1.f + __expf(-x)); }
; DI void gate_tile(const Params& p, int l, int mt, int nt, char* smem) {
;     ...
;   u16* img = (u16*)smem + (wr * 128 + fq * 4) * IMG_LD + wc * 64 + fr;
; #pragma unroll
;   for (int n = 0; n < 4; ++n) {
;     const float bv = bm[n * 16];
; #pragma unroll
;     for (int m = 0; m < 8; ++m)
; #pragma unroll
;       for (int j = 0; j < 4; ++j) {
;         u16* q = img + (m * 16 + j) * IMG_LD + n * 16;
;         *q = f2bf(sigmoidf_(acc[m][n][j] + bv) * bf2f(*q));
;       }
;   }
	v_lshlrev_b32_e32 v138, 16, v138
	v_lshlrev_b32_e32 v139, 16, v139
	v_lshlrev_b32_e32 v140, 16, v140
	v_lshlrev_b32_e32 v141, 16, v141
	v_pk_mul_f32 v[28:29], v[28:29], v[138:139]
	v_pk_mul_f32 v[30:31], v[30:31], v[140:141]
	v_cvt_pk_bf16_f32 v146, v28, v29
	v_cvt_pk_bf16_f32 v147, v30, v31
	ds_write_b16 v2, v146 offset:8544
	ds_write_b16_d16_hi v2, v146 offset:9072
	ds_write_b16 v2, v147 offset:9600
	ds_write_b16_d16_hi v2, v147 offset:10128
	ds_read_u16 v138, v2 offset:25440
	ds_read_u16 v139, v2 offset:25968
	ds_read_u16 v140, v2 offset:26496
	ds_read_u16 v141, v2 offset:27024
	s_waitcnt lgkmcnt(8)
	v_lshlrev_b32_e32 v134, 16, v134
	v_lshlrev_b32_e32 v135, 16, v135
	v_lshlrev_b32_e32 v136, 16, v136
	v_lshlrev_b32_e32 v137, 16, v137
	v_pk_mul_f32 v[24:25], v[24:25], v[134:135]
	v_pk_mul_f32 v[26:27], v[26:27], v[136:137]
	v_cvt_pk_bf16_f32 v146, v24, v25
	v_cvt_pk_bf16_f32 v147, v26, v27
	ds_write_b16 v2, v146 offset:16992
	ds_write_b16_d16_hi v2, v146 offset:17520
	ds_write_b16 v2, v147 offset:18048
	ds_write_b16_d16_hi v2, v147 offset:18576
	ds_read_u16 v134, v2 offset:33888
	ds_read_u16 v135, v2 offset:34416
	ds_read_u16 v136, v2 offset:34944
	ds_read_u16 v137, v2 offset:35472
	s_waitcnt lgkmcnt(8)
	v_lshlrev_b32_e32 v138, 16, v138
	v_lshlrev_b32_e32 v139, 16, v139
	v_lshlrev_b32_e32 v140, 16, v140
	v_lshlrev_b32_e32 v141, 16, v141
	v_pk_mul_f32 v[20:21], v[20:21], v[138:139]
	v_pk_mul_f32 v[22:23], v[22:23], v[140:141]
	v_cvt_pk_bf16_f32 v146, v20, v21
	v_cvt_pk_bf16_f32 v147, v22, v23
	ds_write_b16 v2, v146 offset:25440
	ds_write_b16_d16_hi v2, v146 offset:25968
	ds_write_b16 v2, v147 offset:26496
	ds_write_b16_d16_hi v2, v147 offset:27024
	ds_read_u16 v138, v2 offset:42336
	ds_read_u16 v139, v2 offset:42864
	ds_read_u16 v140, v2 offset:43392
	ds_read_u16 v141, v2 offset:43920
	s_waitcnt lgkmcnt(8)
	v_lshlrev_b32_e32 v134, 16, v134
	v_lshlrev_b32_e32 v135, 16, v135
	v_lshlrev_b32_e32 v136, 16, v136
	v_lshlrev_b32_e32 v137, 16, v137
	v_pk_mul_f32 v[16:17], v[16:17], v[134:135]
	v_pk_mul_f32 v[18:19], v[18:19], v[136:137]
	v_cvt_pk_bf16_f32 v146, v16, v17
	v_cvt_pk_bf16_f32 v147, v18, v19
	ds_write_b16 v2, v146 offset:33888
	ds_write_b16_d16_hi v2, v146 offset:34416
	ds_write_b16 v2, v147 offset:34944
	ds_write_b16_d16_hi v2, v147 offset:35472
	ds_read_u16 v134, v2 offset:50784
	ds_read_u16 v135, v2 offset:51312
	ds_read_u16 v136, v2 offset:51840
	ds_read_u16 v137, v2 offset:52368
	s_waitcnt lgkmcnt(8)
	v_lshlrev_b32_e32 v138, 16, v138
	v_lshlrev_b32_e32 v139, 16, v139
	v_lshlrev_b32_e32 v140, 16, v140
	v_lshlrev_b32_e32 v141, 16, v141
	v_pk_mul_f32 v[12:13], v[12:13], v[138:139]
	v_pk_mul_f32 v[14:15], v[14:15], v[140:141]
	v_cvt_pk_bf16_f32 v146, v12, v13
	v_cvt_pk_bf16_f32 v147, v14, v15
	ds_write_b16 v2, v146 offset:42336
	ds_write_b16_d16_hi v2, v146 offset:42864
	ds_write_b16 v2, v147 offset:43392
	ds_write_b16_d16_hi v2, v147 offset:43920
	ds_read_u16 v138, v2 offset:59232
	ds_read_u16 v139, v2 offset:59760
	ds_read_u16 v140, v2 offset:60288
	ds_read_u16 v141, v2 offset:60816
	s_waitcnt lgkmcnt(8)
	v_lshlrev_b32_e32 v134, 16, v134
	v_lshlrev_b32_e32 v135, 16, v135
	v_lshlrev_b32_e32 v136, 16, v136
	v_lshlrev_b32_e32 v137, 16, v137
	v_pk_mul_f32 v[8:9], v[8:9], v[134:135]
	v_pk_mul_f32 v[10:11], v[10:11], v[136:137]
	v_cvt_pk_bf16_f32 v146, v8, v9
	v_cvt_pk_bf16_f32 v147, v10, v11
	ds_write_b16 v2, v146 offset:50784
	ds_write_b16_d16_hi v2, v146 offset:51312
	ds_write_b16 v2, v147 offset:51840
	ds_write_b16_d16_hi v2, v147 offset:52368
	s_waitcnt lgkmcnt(4)
	v_lshlrev_b32_e32 v138, 16, v138
	v_lshlrev_b32_e32 v139, 16, v139
	v_lshlrev_b32_e32 v140, 16, v140
	v_lshlrev_b32_e32 v141, 16, v141
	v_pk_mul_f32 v[4:5], v[4:5], v[138:139]
	v_pk_mul_f32 v[6:7], v[6:7], v[140:141]
	v_cvt_pk_bf16_f32 v146, v4, v5
	v_cvt_pk_bf16_f32 v147, v6, v7
	ds_write_b16 v2, v146 offset:59232
	ds_write_b16_d16_hi v2, v146 offset:59760
	ds_write_b16 v2, v147 offset:60288
	ds_write_b16_d16_hi v2, v147 offset:60816
	v_mov_b32_e32 v1, v184
	s_waitcnt lgkmcnt(0)
	s_barrier
; DI int TID512() { int t = threadIdx.x; asm volatile("" : "+v"(t)); return t; }
; DI void img_store_bf16(u16* dst, int ld, const char* smem, int rowoff) {
;   const int tid = TID512();
; #pragma unroll
;   for (int q = 0; q < 16; ++q) {
;     const int slot = tid + q * 512, row = slot >> 5, c16 = slot & 31;
;     *(u32x4*)(dst + (size_t)row * ld + c16 * 8) = *(const u32x4*)(smem + (row + rowoff) * (IMG_LD * 2) + c16 * 16);
;   }
; }
	s_nop 0
	v_lshlrev_b32_e32 v0, 4, v1
	v_and_b32_e32 v172, 0x1f0, v0
	v_add_u32_e32 v0, 16, v172
	v_ashrrev_i32_e32 v2, 5, v1
	v_mad_u64_u32 v[4:5], s[4:5], v2, s3, v[0:1]
	ds_read_b128 v[4:7], v4
	v_lshl_add_u64 v[8:9], s[38:39], 0, v[172:173]
	v_mad_i64_i32 v[10:11], s[4:5], v2, s97, v[8:9]
	v_add_u32_e32 v2, 0x200, v1
	v_ashrrev_i32_e32 v2, 5, v2
	s_waitcnt lgkmcnt(0)
	global_store_dwordx4 v[10:11], v[4:7], off
	v_mad_i64_i32 v[10:11], s[4:5], v2, s97, v[8:9]
	s_nop 0
	v_mad_u64_u32 v[4:5], s[4:5], v2, s3, v[0:1]
	ds_read_b128 v[4:7], v4
	v_add_u32_e32 v2, 0x400, v1
	v_ashrrev_i32_e32 v2, 5, v2
	s_waitcnt lgkmcnt(0)
	global_store_dwordx4 v[10:11], v[4:7], off
	s_nop 1
	v_mad_u64_u32 v[4:5], s[4:5], v2, s3, v[0:1]
	ds_read_b128 v[4:7], v4
	v_mad_i64_i32 v[10:11], s[4:5], v2, s97, v[8:9]
	v_add_u32_e32 v2, 0x600, v1
	v_ashrrev_i32_e32 v2, 5, v2
	s_waitcnt lgkmcnt(0)
	global_store_dwordx4 v[10:11], v[4:7], off
	v_mad_i64_i32 v[10:11], s[4:5], v2, s97, v[8:9]
	s_nop 0
	v_mad_u64_u32 v[4:5], s[4:5], v2, s3, v[0:1]
	ds_read_b128 v[4:7], v4
	v_add_u32_e32 v2, 0x800, v1
	v_ashrrev_i32_e32 v2, 5, v2
	s_waitcnt lgkmcnt(0)
	global_store_dwordx4 v[10:11], v[4:7], off
	s_nop 1
	v_mad_u64_u32 v[4:5], s[4:5], v2, s3, v[0:1]
	ds_read_b128 v[4:7], v4
	v_mad_i64_i32 v[10:11], s[4:5], v2, s97, v[8:9]
	v_add_u32_e32 v2, 0xa00, v1
	v_ashrrev_i32_e32 v2, 5, v2
	s_waitcnt lgkmcnt(0)
	global_store_dwordx4 v[10:11], v[4:7], off
	v_mad_i64_i32 v[10:11], s[4:5], v2, s97, v[8:9]
	s_nop 0
	v_mad_u64_u32 v[4:5], s[4:5], v2, s3, v[0:1]
	ds_read_b128 v[4:7], v4
	v_add_u32_e32 v2, 0xc00, v1
	v_ashrrev_i32_e32 v2, 5, v2
	s_waitcnt lgkmcnt(0)
	global_store_dwordx4 v[10:11], v[4:7], off
	s_nop 1
	v_mad_u64_u32 v[4:5], s[4:5], v2, s3, v[0:1]
	ds_read_b128 v[4:7], v4
	v_mad_i64_i32 v[10:11], s[4:5], v2, s97, v[8:9]
	v_add_u32_e32 v2, 0xe00, v1
	v_ashrrev_i32_e32 v2, 5, v2
	s_waitcnt lgkmcnt(0)
	global_store_dwordx4 v[10:11], v[4:7], off
	v_mad_i64_i32 v[10:11], s[4:5], v2, s97, v[8:9]
	s_nop 0
	v_mad_u64_u32 v[4:5], s[4:5], v2, s3, v[0:1]
	ds_read_b128 v[4:7], v4
	v_add_u32_e32 v2, 0x1000, v1
	v_ashrrev_i32_e32 v2, 5, v2
	s_waitcnt lgkmcnt(0)
	global_store_dwordx4 v[10:11], v[4:7], off
	s_nop 1
	v_mad_u64_u32 v[4:5], s[4:5], v2, s3, v[0:1]
	ds_read_b128 v[4:7], v4
	v_mad_i64_i32 v[10:11], s[4:5], v2, s97, v[8:9]
	v_add_u32_e32 v2, 0x1200, v1
	v_ashrrev_i32_e32 v2, 5, v2
	s_waitcnt lgkmcnt(0)
	global_store_dwordx4 v[10:11], v[4:7], off
	v_mad_i64_i32 v[10:11], s[4:5], v2, s97, v[8:9]
	s_nop 0
	v_mad_u64_u32 v[4:5], s[4:5], v2, s3, v[0:1]
	ds_read_b128 v[4:7], v4
	v_add_u32_e32 v2, 0x1400, v1
	v_ashrrev_i32_e32 v2, 5, v2
	s_waitcnt lgkmcnt(0)
	global_store_dwordx4 v[10:11], v[4:7], off
	s_nop 1
	v_mad_u64_u32 v[4:5], s[4:5], v2, s3, v[0:1]
	ds_read_b128 v[4:7], v4
	v_mad_i64_i32 v[10:11], s[4:5], v2, s97, v[8:9]
	v_add_u32_e32 v2, 0x1600, v1
	v_ashrrev_i32_e32 v2, 5, v2
	s_waitcnt lgkmcnt(0)
	global_store_dwordx4 v[10:11], v[4:7], off
	v_mad_i64_i32 v[10:11], s[4:5], v2, s97, v[8:9]
	s_nop 0
	v_mad_u64_u32 v[4:5], s[4:5], v2, s3, v[0:1]
	ds_read_b128 v[4:7], v4
	v_add_u32_e32 v2, 0x1800, v1
	v_ashrrev_i32_e32 v2, 5, v2
	s_waitcnt lgkmcnt(0)
	global_store_dwordx4 v[10:11], v[4:7], off
	s_nop 1
	v_mad_u64_u32 v[4:5], s[4:5], v2, s3, v[0:1]
	ds_read_b128 v[4:7], v4
	v_mad_i64_i32 v[10:11], s[4:5], v2, s97, v[8:9]
	v_add_u32_e32 v2, 0x1a00, v1
	v_ashrrev_i32_e32 v2, 5, v2
	s_waitcnt lgkmcnt(0)
	global_store_dwordx4 v[10:11], v[4:7], off
	v_mad_i64_i32 v[10:11], s[4:5], v2, s97, v[8:9]
	s_nop 0
	v_mad_u64_u32 v[4:5], s[4:5], v2, s3, v[0:1]
	ds_read_b128 v[4:7], v4
	v_add_u32_e32 v2, 0x1c00, v1
	v_ashrrev_i32_e32 v2, 5, v2
	s_waitcnt lgkmcnt(0)
	global_store_dwordx4 v[10:11], v[4:7], off
	s_nop 1
	v_mad_u64_u32 v[4:5], s[4:5], v2, s3, v[0:1]
	ds_read_b128 v[4:7], v4
	v_add_u32_e32 v1, 0x1e00, v1
	v_mad_i64_i32 v[10:11], s[4:5], v2, s97, v[8:9]
	v_ashrrev_i32_e32 v2, 5, v1
	v_mad_u64_u32 v[0:1], s[4:5], v2, s3, v[0:1]
	s_waitcnt lgkmcnt(0)
	global_store_dwordx4 v[10:11], v[4:7], off
	ds_read_b128 v[4:7], v0
	v_mad_i64_i32 v[0:1], s[4:5], v2, s97, v[8:9]
	s_waitcnt lgkmcnt(0)
	global_store_dwordx4 v[0:1], v[4:7], off

; DI int TID512() { int t = threadIdx.x; asm volatile("" : "+v"(t)); return t; }
; DI float bf2f(u16 h) { return __uint_as_float(((unsigned)h) << 16); }
; DI float sigmoidf_(float x) { return __builtin_amdgcn_rcpf(1.f + __expf(-x)); }
; DI void img_load_bf16(const u16* src, int ld, char* smem, int nrows, int rowoff) {
;   for (int slot = TID512(); slot < nrows * 32; slot += 512) {
;     const int row = slot >> 5, c16 = slot & 31;
;     *(u32x4*)(smem + (row + rowoff) * (IMG_LD * 2) + c16 * 16) = __builtin_nontemporal_load((const u32x4*)(src + (size_t)row * ld + c16 * 8));
;   }
; DI void gate_tile(const Params& p, int l, int mt, int nt, char* smem) {
;     ...
;   for (int n = 0; n < 4; ++n) {
;     const float bv = bm[n * 16];
; #pragma unroll
;     for (int m = 0; m < 8; ++m)
; #pragma unroll
;       for (int j = 0; j < 4; ++j) {
;         u16* q = img + (m * 16 + j) * IMG_LD + n * 16;
;         *q = f2bf(sigmoidf_(acc[m][n][j] + bv) * bf2f(*q));
.LBB0_2029:
	v_ashrrev_i32_e32 v138, 5, v133
	v_mad_i64_i32 v[134:135], s[24:25], v138, s97, v[0:1]
	v_mad_u64_u32 v[138:139], s[24:25], v138, s3, v[2:3]
	s_lshl_b32 s34, s97, 4
	s_mov_b32 s35, 0
	s_lshl_b32 s32, s3, 4
	global_load_dwordx4 v[140:143], v[134:135], off nt
	v_lshl_add_u64 v[134:135], v[134:135], 0, s[34:35]
	global_load_dwordx4 v[144:147], v[134:135], off nt
	v_lshl_add_u64 v[134:135], v[134:135], 0, s[34:35]
	global_load_dwordx4 v[148:151], v[134:135], off nt
	v_lshl_add_u64 v[134:135], v[134:135], 0, s[34:35]
	global_load_dwordx4 v[152:155], v[134:135], off nt
	v_lshl_add_u64 v[134:135], v[134:135], 0, s[34:35]
	global_load_dwordx4 v[156:159], v[134:135], off nt
	v_lshl_add_u64 v[134:135], v[134:135], 0, s[34:35]
	global_load_dwordx4 v[160:163], v[134:135], off nt
	v_lshl_add_u64 v[134:135], v[134:135], 0, s[34:35]
	global_load_dwordx4 v[164:167], v[134:135], off nt
	v_lshl_add_u64 v[134:135], v[134:135], 0, s[34:35]
	global_load_dwordx4 v[168:171], v[134:135], off nt
	v_lshl_add_u64 v[134:135], v[134:135], 0, s[34:35]
	global_load_dwordx4 v[176:179], v[134:135], off nt
	v_lshl_add_u64 v[134:135], v[134:135], 0, s[34:35]
	global_load_dwordx4 v[180:183], v[134:135], off nt
	v_lshl_add_u64 v[134:135], v[134:135], 0, s[34:35]
	global_load_dwordx4 v[198:201], v[134:135], off nt
	v_lshl_add_u64 v[134:135], v[134:135], 0, s[34:35]
	global_load_dwordx4 v[202:205], v[134:135], off nt
	v_lshl_add_u64 v[134:135], v[134:135], 0, s[34:35]
	global_load_dwordx4 v[206:209], v[134:135], off nt
	v_lshl_add_u64 v[134:135], v[134:135], 0, s[34:35]
	global_load_dwordx4 v[214:217], v[134:135], off nt
	v_lshl_add_u64 v[134:135], v[134:135], 0, s[34:35]
	global_load_dwordx4 v[218:221], v[134:135], off nt
	v_lshl_add_u64 v[134:135], v[134:135], 0, s[34:35]
	global_load_dwordx4 v[222:225], v[134:135], off nt
	v_lshl_add_u64 v[134:135], v[134:135], 0, s[34:35]
	v_mov_b32_e32 v240, 0xbfb8aa3b
	v_mov_b32_e32 v241, 0xbfb8aa3b
	v_mov_b32_e32 v242, 1.0
	v_mov_b32_e32 v243, 1.0
	s_waitcnt vmcnt(16)
	v_mov_b32_e32 v232, v226
	v_mov_b32_e32 v233, v226
	v_mov_b32_e32 v234, v227
	v_mov_b32_e32 v235, v227
	v_mov_b32_e32 v236, v228
	v_mov_b32_e32 v237, v228
	v_mov_b32_e32 v238, v229
	v_mov_b32_e32 v239, v229
	v_pk_add_f32 v[128:129], v[128:129], v[232:233]
	v_pk_add_f32 v[130:131], v[130:131], v[232:233]
	v_pk_mul_f32 v[128:129], v[240:241], v[128:129]
	v_pk_mul_f32 v[130:131], v[240:241], v[130:131]
	v_exp_f32_e32 v128, v128
	v_exp_f32_e32 v129, v129
	v_exp_f32_e32 v130, v130
	v_exp_f32_e32 v131, v131
	v_pk_add_f32 v[128:129], v[242:243], v[128:129]
	v_pk_add_f32 v[130:131], v[242:243], v[130:131]
	v_rcp_f32_e32 v128, v128
	v_rcp_f32_e32 v129, v129
	v_rcp_f32_e32 v130, v130
	v_rcp_f32_e32 v131, v131
	v_pk_add_f32 v[124:125], v[124:125], v[232:233]
	v_pk_add_f32 v[126:127], v[126:127], v[232:233]
	v_pk_mul_f32 v[124:125], v[240:241], v[124:125]
	v_pk_mul_f32 v[126:127], v[240:241], v[126:127]
	v_exp_f32_e32 v124, v124
	v_exp_f32_e32 v125, v125
	v_exp_f32_e32 v126, v126
	v_exp_f32_e32 v127, v127
	v_pk_add_f32 v[124:125], v[242:243], v[124:125]
	v_pk_add_f32 v[126:127], v[242:243], v[126:127]
	v_rcp_f32_e32 v124, v124
	v_rcp_f32_e32 v125, v125
	v_rcp_f32_e32 v126, v126
	v_rcp_f32_e32 v127, v127
	v_pk_add_f32 v[120:121], v[120:121], v[232:233]
	v_pk_add_f32 v[122:123], v[122:123], v[232:233]
	v_pk_mul_f32 v[120:121], v[240:241], v[120:121]
	v_pk_mul_f32 v[122:123], v[240:241], v[122:123]
	v_exp_f32_e32 v120, v120
	v_exp_f32_e32 v121, v121
	v_exp_f32_e32 v122, v122
	v_exp_f32_e32 v123, v123
	v_pk_add_f32 v[120:121], v[242:243], v[120:121]
	v_pk_add_f32 v[122:123], v[242:243], v[122:123]
	v_rcp_f32_e32 v120, v120
	v_rcp_f32_e32 v121, v121
	v_rcp_f32_e32 v122, v122
	v_rcp_f32_e32 v123, v123
	v_pk_add_f32 v[116:117], v[116:117], v[232:233]
	v_pk_add_f32 v[118:119], v[118:119], v[232:233]
	v_pk_mul_f32 v[116:117], v[240:241], v[116:117]
	v_pk_mul_f32 v[118:119], v[240:241], v[118:119]
	v_exp_f32_e32 v116, v116
	v_exp_f32_e32 v117, v117
	v_exp_f32_e32 v118, v118
	v_exp_f32_e32 v119, v119
	v_pk_add_f32 v[116:117], v[242:243], v[116:117]
	v_pk_add_f32 v[118:119], v[242:243], v[118:119]
	v_rcp_f32_e32 v116, v116
	v_rcp_f32_e32 v117, v117
	v_rcp_f32_e32 v118, v118
	v_rcp_f32_e32 v119, v119
	v_pk_add_f32 v[112:113], v[112:113], v[232:233]
	v_pk_add_f32 v[114:115], v[114:115], v[232:233]
	v_pk_mul_f32 v[112:113], v[240:241], v[112:113]
	v_pk_mul_f32 v[114:115], v[240:241], v[114:115]
	v_exp_f32_e32 v112, v112
	v_exp_f32_e32 v113, v113
	v_exp_f32_e32 v114, v114
	v_exp_f32_e32 v115, v115
	v_pk_add_f32 v[112:113], v[242:243], v[112:113]
	v_pk_add_f32 v[114:115], v[242:243], v[114:115]
	v_rcp_f32_e32 v112, v112
	v_rcp_f32_e32 v113, v113
	v_rcp_f32_e32 v114, v114
	v_rcp_f32_e32 v115, v115
	v_pk_add_f32 v[108:109], v[108:109], v[232:233]
	v_pk_add_f32 v[110:111], v[110:111], v[232:233]
	v_pk_mul_f32 v[108:109], v[240:241], v[108:109]
	v_pk_mul_f32 v[110:111], v[240:241], v[110:111]
	v_exp_f32_e32 v108, v108
	v_exp_f32_e32 v109, v109
	v_exp_f32_e32 v110, v110
	v_exp_f32_e32 v111, v111
	v_pk_add_f32 v[108:109], v[242:243], v[108:109]
	v_pk_add_f32 v[110:111], v[242:243], v[110:111]
	v_rcp_f32_e32 v108, v108
	v_rcp_f32_e32 v109, v109
	v_rcp_f32_e32 v110, v110
	v_rcp_f32_e32 v111, v111
	v_pk_add_f32 v[104:105], v[104:105], v[232:233]
	v_pk_add_f32 v[106:107], v[106:107], v[232:233]
	v_pk_mul_f32 v[104:105], v[240:241], v[104:105]
	v_pk_mul_f32 v[106:107], v[240:241], v[106:107]
	v_exp_f32_e32 v104, v104
	v_exp_f32_e32 v105, v105
	v_exp_f32_e32 v106, v106
	v_exp_f32_e32 v107, v107
	v_pk_add_f32 v[104:105], v[242:243], v[104:105]
	v_pk_add_f32 v[106:107], v[242:243], v[106:107]
; DI float bf2f(u16 h) { return __uint_as_float(((unsigned)h) << 16); }
; DI float sigmoidf_(float x) { return __builtin_amdgcn_rcpf(1.f + __expf(-x)); }
; DI void gate_tile(const Params& p, int l, int mt, int nt, char* smem) {
;     ...
;   for (int n = 0; n < 4; ++n) {
;     const float bv = bm[n * 16];
; #pragma unroll
;     for (int m = 0; m < 8; ++m)
; #pragma unroll
;       for (int j = 0; j < 4; ++j) {
;         u16* q = img + (m * 16 + j) * IMG_LD + n * 16;
;         *q = f2bf(sigmoidf_(acc[m][n][j] + bv) * bf2f(*q));
	v_rcp_f32_e32 v104, v104
	v_rcp_f32_e32 v105, v105
	v_rcp_f32_e32 v106, v106
	v_rcp_f32_e32 v107, v107
	v_pk_add_f32 v[100:101], v[100:101], v[232:233]
	v_pk_add_f32 v[102:103], v[102:103], v[232:233]
	v_pk_mul_f32 v[100:101], v[240:241], v[100:101]
	v_pk_mul_f32 v[102:103], v[240:241], v[102:103]
	v_exp_f32_e32 v100, v100
	v_exp_f32_e32 v101, v101
	v_exp_f32_e32 v102, v102
	v_exp_f32_e32 v103, v103
	v_pk_add_f32 v[100:101], v[242:243], v[100:101]
	v_pk_add_f32 v[102:103], v[242:243], v[102:103]
	v_rcp_f32_e32 v100, v100
	v_rcp_f32_e32 v101, v101
	v_rcp_f32_e32 v102, v102
	v_rcp_f32_e32 v103, v103
	v_pk_add_f32 v[96:97], v[96:97], v[234:235]
	v_pk_add_f32 v[98:99], v[98:99], v[234:235]
	v_pk_mul_f32 v[96:97], v[240:241], v[96:97]
	v_pk_mul_f32 v[98:99], v[240:241], v[98:99]
	v_exp_f32_e32 v96, v96
	v_exp_f32_e32 v97, v97
	v_exp_f32_e32 v98, v98
	v_exp_f32_e32 v99, v99
	v_pk_add_f32 v[96:97], v[242:243], v[96:97]
	v_pk_add_f32 v[98:99], v[242:243], v[98:99]
	v_rcp_f32_e32 v96, v96
	v_rcp_f32_e32 v97, v97
	v_rcp_f32_e32 v98, v98
	v_rcp_f32_e32 v99, v99
	v_pk_add_f32 v[92:93], v[92:93], v[234:235]
	v_pk_add_f32 v[94:95], v[94:95], v[234:235]
	v_pk_mul_f32 v[92:93], v[240:241], v[92:93]
	v_pk_mul_f32 v[94:95], v[240:241], v[94:95]
	v_exp_f32_e32 v92, v92
	v_exp_f32_e32 v93, v93
	v_exp_f32_e32 v94, v94
	v_exp_f32_e32 v95, v95
	v_pk_add_f32 v[92:93], v[242:243], v[92:93]
	v_pk_add_f32 v[94:95], v[242:243], v[94:95]
	v_rcp_f32_e32 v92, v92
	v_rcp_f32_e32 v93, v93
	v_rcp_f32_e32 v94, v94
	v_rcp_f32_e32 v95, v95
	v_pk_add_f32 v[88:89], v[88:89], v[234:235]
	v_pk_add_f32 v[90:91], v[90:91], v[234:235]
	v_pk_mul_f32 v[88:89], v[240:241], v[88:89]
	v_pk_mul_f32 v[90:91], v[240:241], v[90:91]
	v_exp_f32_e32 v88, v88
	v_exp_f32_e32 v89, v89
	v_exp_f32_e32 v90, v90
	v_exp_f32_e32 v91, v91
	v_pk_add_f32 v[88:89], v[242:243], v[88:89]
	v_pk_add_f32 v[90:91], v[242:243], v[90:91]
	v_rcp_f32_e32 v88, v88
	v_rcp_f32_e32 v89, v89
	v_rcp_f32_e32 v90, v90
	v_rcp_f32_e32 v91, v91
	v_pk_add_f32 v[84:85], v[84:85], v[234:235]
	v_pk_add_f32 v[86:87], v[86:87], v[234:235]
	v_pk_mul_f32 v[84:85], v[240:241], v[84:85]
	v_pk_mul_f32 v[86:87], v[240:241], v[86:87]
	v_exp_f32_e32 v84, v84
	v_exp_f32_e32 v85, v85
	v_exp_f32_e32 v86, v86
	v_exp_f32_e32 v87, v87
	v_pk_add_f32 v[84:85], v[242:243], v[84:85]
	v_pk_add_f32 v[86:87], v[242:243], v[86:87]
	v_rcp_f32_e32 v84, v84
	v_rcp_f32_e32 v85, v85
	v_rcp_f32_e32 v86, v86
	v_rcp_f32_e32 v87, v87
	v_pk_add_f32 v[80:81], v[80:81], v[234:235]
	v_pk_add_f32 v[82:83], v[82:83], v[234:235]
	v_pk_mul_f32 v[80:81], v[240:241], v[80:81]
	v_pk_mul_f32 v[82:83], v[240:241], v[82:83]
	v_exp_f32_e32 v80, v80
	v_exp_f32_e32 v81, v81
	v_exp_f32_e32 v82, v82
	v_exp_f32_e32 v83, v83
	v_pk_add_f32 v[80:81], v[242:243], v[80:81]
	v_pk_add_f32 v[82:83], v[242:243], v[82:83]
	v_rcp_f32_e32 v80, v80
	v_rcp_f32_e32 v81, v81
	v_rcp_f32_e32 v82, v82
	v_rcp_f32_e32 v83, v83
	v_pk_add_f32 v[76:77], v[76:77], v[234:235]
	v_pk_add_f32 v[78:79], v[78:79], v[234:235]
	v_pk_mul_f32 v[76:77], v[240:241], v[76:77]
	v_pk_mul_f32 v[78:79], v[240:241], v[78:79]
	v_exp_f32_e32 v76, v76
	v_exp_f32_e32 v77, v77
	v_exp_f32_e32 v78, v78
	v_exp_f32_e32 v79, v79
	v_pk_add_f32 v[76:77], v[242:243], v[76:77]
	v_pk_add_f32 v[78:79], v[242:243], v[78:79]
	v_rcp_f32_e32 v76, v76
	v_rcp_f32_e32 v77, v77
	v_rcp_f32_e32 v78, v78
	v_rcp_f32_e32 v79, v79
	v_pk_add_f32 v[72:73], v[72:73], v[234:235]
	v_pk_add_f32 v[74:75], v[74:75], v[234:235]
	v_pk_mul_f32 v[72:73], v[240:241], v[72:73]
	v_pk_mul_f32 v[74:75], v[240:241], v[74:75]
	v_exp_f32_e32 v72, v72
	v_exp_f32_e32 v73, v73
	v_exp_f32_e32 v74, v74
	v_exp_f32_e32 v75, v75
	v_pk_add_f32 v[72:73], v[242:243], v[72:73]
	v_pk_add_f32 v[74:75], v[242:243], v[74:75]
	v_rcp_f32_e32 v72, v72
	v_rcp_f32_e32 v73, v73
	v_rcp_f32_e32 v74, v74
	v_rcp_f32_e32 v75, v75
	v_pk_add_f32 v[68:69], v[68:69], v[234:235]
	v_pk_add_f32 v[70:71], v[70:71], v[234:235]
	v_pk_mul_f32 v[68:69], v[240:241], v[68:69]
	v_pk_mul_f32 v[70:71], v[240:241], v[70:71]
	v_exp_f32_e32 v68, v68
	v_exp_f32_e32 v69, v69
	v_exp_f32_e32 v70, v70
	v_exp_f32_e32 v71, v71
	v_pk_add_f32 v[68:69], v[242:243], v[68:69]
	v_pk_add_f32 v[70:71], v[242:243], v[70:71]
	v_rcp_f32_e32 v68, v68
	v_rcp_f32_e32 v69, v69
	v_rcp_f32_e32 v70, v70
	v_rcp_f32_e32 v71, v71
	v_pk_add_f32 v[64:65], v[64:65], v[236:237]
	v_pk_add_f32 v[66:67], v[66:67], v[236:237]
	v_pk_mul_f32 v[64:65], v[240:241], v[64:65]
	v_pk_mul_f32 v[66:67], v[240:241], v[66:67]
	v_exp_f32_e32 v64, v64
	v_exp_f32_e32 v65, v65
	v_exp_f32_e32 v66, v66
	v_exp_f32_e32 v67, v67
	v_pk_add_f32 v[64:65], v[242:243], v[64:65]
	v_pk_add_f32 v[66:67], v[242:243], v[66:67]
	v_rcp_f32_e32 v64, v64
	v_rcp_f32_e32 v65, v65
	v_rcp_f32_e32 v66, v66
	v_rcp_f32_e32 v67, v67
	v_pk_add_f32 v[60:61], v[60:61], v[236:237]
	v_pk_add_f32 v[62:63], v[62:63], v[236:237]
	v_pk_mul_f32 v[60:61], v[240:241], v[60:61]
	v_pk_mul_f32 v[62:63], v[240:241], v[62:63]
	v_exp_f32_e32 v60, v60
	v_exp_f32_e32 v61, v61
	v_exp_f32_e32 v62, v62
	v_exp_f32_e32 v63, v63
	v_pk_add_f32 v[60:61], v[242:243], v[60:61]
	v_pk_add_f32 v[62:63], v[242:243], v[62:63]
	v_rcp_f32_e32 v60, v60
	v_rcp_f32_e32 v61, v61
	v_rcp_f32_e32 v62, v62
	v_rcp_f32_e32 v63, v63
	v_pk_add_f32 v[56:57], v[56:57], v[236:237]
	v_pk_add_f32 v[58:59], v[58:59], v[236:237]
	v_pk_mul_f32 v[56:57], v[240:241], v[56:57]
	v_pk_mul_f32 v[58:59], v[240:241], v[58:59]
	v_exp_f32_e32 v56, v56
	v_exp_f32_e32 v57, v57
	v_exp_f32_e32 v58, v58
	v_exp_f32_e32 v59, v59
	v_pk_add_f32 v[56:57], v[242:243], v[56:57]
	v_pk_add_f32 v[58:59], v[242:243], v[58:59]
	v_rcp_f32_e32 v56, v56
	v_rcp_f32_e32 v57, v57
; DI float bf2f(u16 h) { return __uint_as_float(((unsigned)h) << 16); }
; DI float sigmoidf_(float x) { return __builtin_amdgcn_rcpf(1.f + __expf(-x)); }
; DI void gate_tile(const Params& p, int l, int mt, int nt, char* smem) {
;     ...
;   for (int n = 0; n < 4; ++n) {
;     const float bv = bm[n * 16];
; #pragma unroll
;     for (int m = 0; m < 8; ++m)
; #pragma unroll
;       for (int j = 0; j < 4; ++j) {
;         u16* q = img + (m * 16 + j) * IMG_LD + n * 16;
;         *q = f2bf(sigmoidf_(acc[m][n][j] + bv) * bf2f(*q));
	v_rcp_f32_e32 v58, v58
	v_rcp_f32_e32 v59, v59
	v_pk_add_f32 v[52:53], v[52:53], v[236:237]
	v_pk_add_f32 v[54:55], v[54:55], v[236:237]
	v_pk_mul_f32 v[52:53], v[240:241], v[52:53]
	v_pk_mul_f32 v[54:55], v[240:241], v[54:55]
	v_exp_f32_e32 v52, v52
	v_exp_f32_e32 v53, v53
	v_exp_f32_e32 v54, v54
	v_exp_f32_e32 v55, v55
	v_pk_add_f32 v[52:53], v[242:243], v[52:53]
	v_pk_add_f32 v[54:55], v[242:243], v[54:55]
	v_rcp_f32_e32 v52, v52
	v_rcp_f32_e32 v53, v53
	v_rcp_f32_e32 v54, v54
	v_rcp_f32_e32 v55, v55
	v_pk_add_f32 v[48:49], v[48:49], v[236:237]
	v_pk_add_f32 v[50:51], v[50:51], v[236:237]
	v_pk_mul_f32 v[48:49], v[240:241], v[48:49]
	v_pk_mul_f32 v[50:51], v[240:241], v[50:51]
	v_exp_f32_e32 v48, v48
	v_exp_f32_e32 v49, v49
	v_exp_f32_e32 v50, v50
	v_exp_f32_e32 v51, v51
	v_pk_add_f32 v[48:49], v[242:243], v[48:49]
	v_pk_add_f32 v[50:51], v[242:243], v[50:51]
	v_rcp_f32_e32 v48, v48
	v_rcp_f32_e32 v49, v49
	v_rcp_f32_e32 v50, v50
	v_rcp_f32_e32 v51, v51
	v_pk_add_f32 v[44:45], v[44:45], v[236:237]
	v_pk_add_f32 v[46:47], v[46:47], v[236:237]
	v_pk_mul_f32 v[44:45], v[240:241], v[44:45]
	v_pk_mul_f32 v[46:47], v[240:241], v[46:47]
	v_exp_f32_e32 v44, v44
	v_exp_f32_e32 v45, v45
	v_exp_f32_e32 v46, v46
	v_exp_f32_e32 v47, v47
	v_pk_add_f32 v[44:45], v[242:243], v[44:45]
	v_pk_add_f32 v[46:47], v[242:243], v[46:47]
	v_rcp_f32_e32 v44, v44
	v_rcp_f32_e32 v45, v45
	v_rcp_f32_e32 v46, v46
	v_rcp_f32_e32 v47, v47
	v_pk_add_f32 v[40:41], v[40:41], v[236:237]
	v_pk_add_f32 v[42:43], v[42:43], v[236:237]
	v_pk_mul_f32 v[40:41], v[240:241], v[40:41]
	v_pk_mul_f32 v[42:43], v[240:241], v[42:43]
	v_exp_f32_e32 v40, v40
	v_exp_f32_e32 v41, v41
	v_exp_f32_e32 v42, v42
	v_exp_f32_e32 v43, v43
	v_pk_add_f32 v[40:41], v[242:243], v[40:41]
	v_pk_add_f32 v[42:43], v[242:243], v[42:43]
	v_rcp_f32_e32 v40, v40
	v_rcp_f32_e32 v41, v41
	v_rcp_f32_e32 v42, v42
	v_rcp_f32_e32 v43, v43
	v_pk_add_f32 v[36:37], v[36:37], v[236:237]
	v_pk_add_f32 v[38:39], v[38:39], v[236:237]
	v_pk_mul_f32 v[36:37], v[240:241], v[36:37]
	v_pk_mul_f32 v[38:39], v[240:241], v[38:39]
	v_exp_f32_e32 v36, v36
	v_exp_f32_e32 v37, v37
	v_exp_f32_e32 v38, v38
	v_exp_f32_e32 v39, v39
	v_pk_add_f32 v[36:37], v[242:243], v[36:37]
	v_pk_add_f32 v[38:39], v[242:243], v[38:39]
	v_rcp_f32_e32 v36, v36
	v_rcp_f32_e32 v37, v37
	v_rcp_f32_e32 v38, v38
	v_rcp_f32_e32 v39, v39
	v_pk_add_f32 v[32:33], v[32:33], v[238:239]
	v_pk_add_f32 v[34:35], v[34:35], v[238:239]
	v_pk_mul_f32 v[32:33], v[240:241], v[32:33]
	v_pk_mul_f32 v[34:35], v[240:241], v[34:35]
	v_exp_f32_e32 v32, v32
	v_exp_f32_e32 v33, v33
	v_exp_f32_e32 v34, v34
	v_exp_f32_e32 v35, v35
	v_pk_add_f32 v[32:33], v[242:243], v[32:33]
	v_pk_add_f32 v[34:35], v[242:243], v[34:35]
	v_rcp_f32_e32 v32, v32
	v_rcp_f32_e32 v33, v33
	v_rcp_f32_e32 v34, v34
	v_rcp_f32_e32 v35, v35
	v_pk_add_f32 v[28:29], v[28:29], v[238:239]
	v_pk_add_f32 v[30:31], v[30:31], v[238:239]
	v_pk_mul_f32 v[28:29], v[240:241], v[28:29]
	v_pk_mul_f32 v[30:31], v[240:241], v[30:31]
	v_exp_f32_e32 v28, v28
	v_exp_f32_e32 v29, v29
	v_exp_f32_e32 v30, v30
	v_exp_f32_e32 v31, v31
	v_pk_add_f32 v[28:29], v[242:243], v[28:29]
	v_pk_add_f32 v[30:31], v[242:243], v[30:31]
	v_rcp_f32_e32 v28, v28
	v_rcp_f32_e32 v29, v29
	v_rcp_f32_e32 v30, v30
	v_rcp_f32_e32 v31, v31
	v_pk_add_f32 v[24:25], v[24:25], v[238:239]
	v_pk_add_f32 v[26:27], v[26:27], v[238:239]
	v_pk_mul_f32 v[24:25], v[240:241], v[24:25]
	v_pk_mul_f32 v[26:27], v[240:241], v[26:27]
	v_exp_f32_e32 v24, v24
	v_exp_f32_e32 v25, v25
	v_exp_f32_e32 v26, v26
	v_exp_f32_e32 v27, v27
	v_pk_add_f32 v[24:25], v[242:243], v[24:25]
	v_pk_add_f32 v[26:27], v[242:243], v[26:27]
	v_rcp_f32_e32 v24, v24
	v_rcp_f32_e32 v25, v25
	v_rcp_f32_e32 v26, v26
	v_rcp_f32_e32 v27, v27
	v_pk_add_f32 v[20:21], v[20:21], v[238:239]
	v_pk_add_f32 v[22:23], v[22:23], v[238:239]
	v_pk_mul_f32 v[20:21], v[240:241], v[20:21]
	v_pk_mul_f32 v[22:23], v[240:241], v[22:23]
	v_exp_f32_e32 v20, v20
	v_exp_f32_e32 v21, v21
	v_exp_f32_e32 v22, v22
	v_exp_f32_e32 v23, v23
	v_pk_add_f32 v[20:21], v[242:243], v[20:21]
	v_pk_add_f32 v[22:23], v[242:243], v[22:23]
	v_rcp_f32_e32 v20, v20
	v_rcp_f32_e32 v21, v21
	v_rcp_f32_e32 v22, v22
	v_rcp_f32_e32 v23, v23
	v_pk_add_f32 v[16:17], v[16:17], v[238:239]
	v_pk_add_f32 v[18:19], v[18:19], v[238:239]
	v_pk_mul_f32 v[16:17], v[240:241], v[16:17]
	v_pk_mul_f32 v[18:19], v[240:241], v[18:19]
	v_exp_f32_e32 v16, v16
	v_exp_f32_e32 v17, v17
	v_exp_f32_e32 v18, v18
	v_exp_f32_e32 v19, v19
	v_pk_add_f32 v[16:17], v[242:243], v[16:17]
	v_pk_add_f32 v[18:19], v[242:243], v[18:19]
	v_rcp_f32_e32 v16, v16
	v_rcp_f32_e32 v17, v17
	v_rcp_f32_e32 v18, v18
	v_rcp_f32_e32 v19, v19
	v_pk_add_f32 v[12:13], v[12:13], v[238:239]
	v_pk_add_f32 v[14:15], v[14:15], v[238:239]
	v_pk_mul_f32 v[12:13], v[240:241], v[12:13]
	v_pk_mul_f32 v[14:15], v[240:241], v[14:15]
	v_exp_f32_e32 v12, v12
	v_exp_f32_e32 v13, v13
	v_exp_f32_e32 v14, v14
	v_exp_f32_e32 v15, v15
	v_pk_add_f32 v[12:13], v[242:243], v[12:13]
	v_pk_add_f32 v[14:15], v[242:243], v[14:15]
	v_rcp_f32_e32 v12, v12
	v_rcp_f32_e32 v13, v13
	v_rcp_f32_e32 v14, v14
	v_rcp_f32_e32 v15, v15
	v_pk_add_f32 v[8:9], v[8:9], v[238:239]
	v_pk_add_f32 v[10:11], v[10:11], v[238:239]
	v_pk_mul_f32 v[8:9], v[240:241], v[8:9]
	v_pk_mul_f32 v[10:11], v[240:241], v[10:11]
	v_exp_f32_e32 v8, v8
	v_exp_f32_e32 v9, v9
	v_exp_f32_e32 v10, v10
	v_exp_f32_e32 v11, v11
	v_pk_add_f32 v[8:9], v[242:243], v[8:9]
	v_pk_add_f32 v[10:11], v[242:243], v[10:11]
	v_rcp_f32_e32 v8, v8
	v_rcp_f32_e32 v9, v9
	v_rcp_f32_e32 v10, v10
	v_rcp_f32_e32 v11, v11
	v_pk_add_f32 v[4:5], v[4:5], v[238:239]
	v_pk_add_f32 v[6:7], v[6:7], v[238:239]
	v_pk_mul_f32 v[4:5], v[240:241], v[4:5]
	v_pk_mul_f32 v[6:7], v[240:241], v[6:7]
	v_exp_f32_e32 v4, v4
	v_exp_f32_e32 v5, v5
	v_exp_f32_e32 v6, v6
	v_exp_f32_e32 v7, v7
	v_pk_add_f32 v[4:5], v[242:243], v[4:5]
	v_pk_add_f32 v[6:7], v[242:243], v[6:7]
	v_rcp_f32_e32 v4, v4
	v_rcp_f32_e32 v5, v5
	v_rcp_f32_e32 v6, v6
	v_rcp_f32_e32 v7, v7
	s_waitcnt vmcnt(15)
; DI int TID512() { int t = threadIdx.x; asm volatile("" : "+v"(t)); return t; }
; DI void img_load_bf16(const u16* src, int ld, char* smem, int nrows, int rowoff) {
;   for (int slot = TID512(); slot < nrows * 32; slot += 512) {
;     const int row = slot >> 5, c16 = slot & 31;
;     *(u32x4*)(smem + (row + rowoff) * (IMG_LD * 2) + c16 * 16) = __builtin_nontemporal_load((const u32x4*)(src + (size_t)row * ld + c16 * 8));
;   }
	ds_write_b128 v138, v[140:143]
	v_add_u32_e32 v138, s32, v138
	s_waitcnt vmcnt(14)
	ds_write_b128 v138, v[144:147]
	v_add_u32_e32 v138, s32, v138
	s_waitcnt vmcnt(13)
	ds_write_b128 v138, v[148:151]
	v_add_u32_e32 v138, s32, v138
	s_waitcnt vmcnt(12)
	ds_write_b128 v138, v[152:155]
	v_add_u32_e32 v138, s32, v138
	s_waitcnt vmcnt(11)
	ds_write_b128 v138, v[156:159]
	v_add_u32_e32 v138, s32, v138
	s_waitcnt vmcnt(10)
	ds_write_b128 v138, v[160:163]
	v_add_u32_e32 v138, s32, v138
	s_waitcnt vmcnt(9)
	ds_write_b128 v138, v[164:167]
	v_add_u32_e32 v138, s32, v138
	s_waitcnt vmcnt(8)
	ds_write_b128 v138, v[168:171]
	v_add_u32_e32 v138, s32, v138
	s_waitcnt vmcnt(7)
	ds_write_b128 v138, v[176:179]
	v_add_u32_e32 v138, s32, v138
	s_waitcnt vmcnt(6)
	ds_write_b128 v138, v[180:183]
	v_add_u32_e32 v138, s32, v138
	s_waitcnt vmcnt(5)
	ds_write_b128 v138, v[198:201]
	v_add_u32_e32 v138, s32, v138
	s_waitcnt vmcnt(4)
	ds_write_b128 v138, v[202:205]
	v_add_u32_e32 v138, s32, v138
	s_waitcnt vmcnt(3)
	ds_write_b128 v138, v[206:209]
	v_add_u32_e32 v138, s32, v138
	s_waitcnt vmcnt(2)
	ds_write_b128 v138, v[214:217]
	v_add_u32_e32 v138, s32, v138
	s_waitcnt vmcnt(1)
	ds_write_b128 v138, v[218:221]
	v_add_u32_e32 v138, s32, v138
	s_waitcnt vmcnt(0)
	ds_write_b128 v138, v[222:225]
	v_add_u32_e32 v138, s32, v138
	s_branch .LBB0_2020

; DI unsigned pack2(float a, float b) { f32v2_t v = {a, b}; bf16v2_t r = __builtin_convertvector(v, bf16v2_t); return __builtin_bit_cast(unsigned, r); }
; DI float wave_sum(float v) {
;   for (int o = 32; o > 0; o >>= 1) v += __shfl_xor(v, o);
;   return v;
; }
; DI void norm_phase(const Params& p, int l, int mode, int B, int G, char* smem) {
;     ...
;   for (int row = B * 8 + wid; row < MT; row += G * 8) {
;     float* X = p.out + (size_t)row * 1024;
;     const float* Xr = (mode == 0 && l == 0 && row < MP) ? p.in[0] + (size_t)row * 1024 : X;
;     float4 v[4];
;     float ss = 0.f;
; #pragma unroll
;     for (int i = 0; i < 4; ++i) { { const f32x4 t4 = __builtin_nontemporal_load((const f32x4*)(Xr + i * 256 + lane * 4)); v[i] = float4{t4[0], t4[1], t4[2], t4[3]}; } ss += v[i].x * v[i].x + v[i].y * v[i].y + v[i].z * v[i].z + v[i].w * v[i].w; }
;     ss = wave_sum(ss);
;     const float rs = rsqrtf(ss * (1.f / 1024.f) + EPS);
;     u16* XN = (u16*)(p.ws + O_XN) + (size_t)row * LDK;
; #pragma unroll
;     for (int i = 0; i < 4; ++i) {
;       v[i] = float4{v[i].x * rs * g[i].x, v[i].y * rs * g[i].y, v[i].z * rs * g[i].z, v[i].w * rs * g[i].w};
;       if (mode == 2) *(float4*)(X + i * 256 + lane * 4) = v[i];
;       else *(uint2*)(XN + i * 256 + lane * 4) = uint2{pack2(v[i].x, v[i].y), pack2(v[i].z, v[i].w)};
;     }
.LBB0_2169:
	s_waitcnt vmcnt(0)
	v_mov_b32_e32 v28, v60
	v_mov_b32_e32 v29, v61
	v_mov_b32_e32 v30, v62
	v_mov_b32_e32 v31, v63
	v_mov_b32_e32 v32, v64
	v_mov_b32_e32 v33, v65
	v_mov_b32_e32 v34, v66
	v_mov_b32_e32 v35, v67
	v_mov_b32_e32 v76, v68
	v_mov_b32_e32 v77, v69
	v_mov_b32_e32 v78, v70
	v_mov_b32_e32 v79, v71
	v_mov_b32_e32 v80, v72
	v_mov_b32_e32 v81, v73
	v_mov_b32_e32 v82, v74
	v_mov_b32_e32 v83, v75
	v_add_u32_e32 v2, s20, v2
	v_cmp_ge_i32_e64 s[34:35], s42, v2
	v_lshl_add_u64 v[84:85], v[20:21], 0, s[38:39]
	s_nop 0
	v_cndmask_b32_e64 v20, v20, v84, s[34:35]
	v_cndmask_b32_e64 v21, v21, v85, s[34:35]
	global_load_dwordx4 v[60:63], v[20:21], off offset:-3072 nt
	global_load_dwordx4 v[64:67], v[20:21], off offset:-2048 nt
	global_load_dwordx4 v[68:71], v[20:21], off offset:-1024 nt
	global_load_dwordx4 v[72:75], v[20:21], off nt
	v_mov_b32_e32 v38, v29
	v_mov_b32_e32 v39, v33
	v_mov_b32_e32 v36, v28
	v_mov_b32_e32 v37, v32
	v_pk_mul_f32 v[38:39], v[38:39], v[38:39]
	s_nop 0
	v_pk_fma_f32 v[36:37], v[36:37], v[36:37], v[38:39]
	v_mov_b32_e32 v38, v30
	v_mov_b32_e32 v39, v34
	v_pk_fma_f32 v[36:37], v[38:39], v[38:39], v[36:37]
	v_mov_b32_e32 v38, v31
	v_mov_b32_e32 v39, v35
	v_pk_fma_f32 v[44:45], v[38:39], v[38:39], v[36:37]
	v_add_f32_e32 v44, v44, v45
	v_mov_b32_e32 v48, v77
	v_mov_b32_e32 v49, v81
	v_mov_b32_e32 v46, v76
	v_mov_b32_e32 v47, v80
	v_pk_mul_f32 v[48:49], v[48:49], v[48:49]
	s_nop 0
	v_pk_fma_f32 v[46:47], v[46:47], v[46:47], v[48:49]
	v_mov_b32_e32 v48, v78
	v_mov_b32_e32 v49, v82
	v_pk_fma_f32 v[46:47], v[48:49], v[48:49], v[46:47]
	v_mov_b32_e32 v48, v79
	v_mov_b32_e32 v49, v83
	v_pk_fma_f32 v[46:47], v[48:49], v[48:49], v[46:47]
	s_nop 0
	v_add_f32_e32 v44, v44, v46
	v_add_f32_e32 v44, v44, v47
	s_nop 1
	v_add_f32_dpp v44, v44, v44 quad_perm:[1,0,3,2] row_mask:0xf bank_mask:0xf
	s_nop 1
	v_add_f32_dpp v44, v44, v44 quad_perm:[2,3,0,1] row_mask:0xf bank_mask:0xf
	s_nop 1
	v_add_f32_dpp v44, v44, v44 row_ror:4 row_mask:0xf bank_mask:0xf
	s_nop 1
	v_add_f32_dpp v44, v44, v44 row_ror:8 row_mask:0xf bank_mask:0xf
	s_nop 0
	v_mov_b32_e32 v45, v44
	s_nop 1
	v_permlane16_swap_b32_e32 v44, v45
	v_add_f32_e32 v44, v44, v45
	v_mov_b32_e32 v45, v44
	s_nop 1
	v_permlane32_swap_b32_e32 v44, v45
	v_add_f32_e32 v44, v44, v45
	v_fmamk_f32 v44, v44, 0x3a800000, v186
	v_cmp_gt_f32_e32 vcc, s1, v44
	v_mul_f32_e32 v45, 0x4b800000, v44
	s_nop 0
	v_cndmask_b32_e32 v44, v44, v45, vcc
	v_rsq_f32_e32 v44, v44
	s_nop 0
	v_mul_f32_e32 v45, 0x45800000, v44
	v_cndmask_b32_e32 v44, v44, v45, vcc
	v_pk_mul_f32 v[28:29], v[28:29], v[44:45] op_sel_hi:[1,0]
	v_pk_mul_f32 v[30:31], v[30:31], v[44:45] op_sel_hi:[1,0]
	v_pk_mul_f32 v[28:29], v[4:5], v[28:29]
	v_pk_mul_f32 v[30:31], v[6:7], v[30:31]
	v_cvt_pk_bf16_f32 v28, v28, v29
	v_cvt_pk_bf16_f32 v29, v30, v31
	global_store_dwordx2 v[0:1], v[28:29], off offset:-1024
	v_pk_mul_f32 v[28:29], v[32:33], v[44:45] op_sel_hi:[1,0]
	v_pk_mul_f32 v[30:31], v[34:35], v[44:45] op_sel_hi:[1,0]
	v_pk_mul_f32 v[28:29], v[8:9], v[28:29]
	v_pk_mul_f32 v[30:31], v[10:11], v[30:31]
	v_cvt_pk_bf16_f32 v28, v28, v29
	v_cvt_pk_bf16_f32 v29, v30, v31
	global_store_dwordx2 v[0:1], v[28:29], off offset:-512
	v_pk_mul_f32 v[28:29], v[76:77], v[44:45] op_sel_hi:[1,0]
	v_pk_mul_f32 v[30:31], v[78:79], v[44:45] op_sel_hi:[1,0]
	v_pk_mul_f32 v[28:29], v[12:13], v[28:29]
	v_pk_mul_f32 v[30:31], v[14:15], v[30:31]
	v_cvt_pk_bf16_f32 v28, v28, v29
	v_cvt_pk_bf16_f32 v29, v30, v31
	global_store_dwordx2 v[0:1], v[28:29], off
	v_pk_mul_f32 v[28:29], v[80:81], v[44:45] op_sel_hi:[1,0]
	v_pk_mul_f32 v[30:31], v[82:83], v[44:45] op_sel_hi:[1,0]
	v_pk_mul_f32 v[28:29], v[16:17], v[28:29]
	v_pk_mul_f32 v[30:31], v[18:19], v[30:31]
	v_cvt_pk_bf16_f32 v28, v28, v29
	v_cvt_pk_bf16_f32 v29, v30, v31
	v_cmp_lt_i32_e32 vcc, s42, v2
	global_store_dwordx2 v[0:1], v[28:29], off offset:512
	v_lshl_add_u64 v[0:1], v[0:1], 0, s[40:41]
	s_or_b64 s[6:7], vcc, s[6:7]
	s_andn2_b64 exec, exec, s[6:7]
	s_cbranch_execnz .LBB0_2169
